# P6: second half of the SwiGLU epilogue moved into the next unit's peeled first K-iteration (same as P1)
# baseline (speedup 1.0000x reference)
; #define PG8_STAGE(bufoff, gbase, voff) do { _Pragma("unroll") for (int _i = 0; _i < 2; ++_i) \
;         __builtin_amdgcn_global_load_lds((const unsigned*)((const char*)(gbase) + (voff)[_i]), (PG8_LAS unsigned*)(lds + (bufoff) + ldsw + _i * 8192), 16, 0, 0); } while (0)
; #define PG8_WAIT_V(n) asm volatile("s_waitcnt vmcnt(" #n ")" ::: "memory")
; #define PG8_BAR __builtin_amdgcn_s_barrier()
; template <class Epi, class Sched, bool ALIGN_EPI = false, bool SP2 = false>
; __device__ __forceinline__ void gemm_phase(PG8_LAS unsigned char* lds, const Gemm g, const Sched& S, const Epi& E) {
;     ...
;     const int aoff = lds_byte(wr * 64 + fr, fq * 8), boff = lds_byte(wc * 32 + fr, fq * 8);
;     ...
;         PG8_STAGE(PG8_SB(0, 0), cB, voffB); PG8_STAGE(PG8_SB(0, 1), cB + hstep, voffB); PG8_STAGE(PG8_SA(0, 0), cA, voffA); PG8_STAGE(PG8_SA(0, 1), cA + hstep, voffA);
;         if (wr == 1) PG8_BAR;
;         PG8_WAIT_V(2); PG8_BAR;
;         PG8_STAGE(PG8_SB(1, 0), cB + kstep, voffB); PG8_STAGE(PG8_SA(1, 0), cA + kstep, voffA); PG8_STAGE(PG8_SB(1, 1), cB + hstep + kstep, voffB);
;         PG8_WAIT_V(6); PG8_BAR;
.LBB0_776:
	s_lshl_b32 s1, s6, 5
	s_mov_b64 s[6:7], 0x80
	s_and_b32 s16, s1, 0x60
	s_add_i32 m0, s34, 0x18000
	v_lshl_add_u64 v[6:7], v[6:7], 0, s[6:7]
	s_lshl_b32 s13, s12, 13
	s_lshl_b32 s17, s16, 7
	s_waitcnt vmcnt(2)
	s_barrier
	global_load_lds_dwordx4 v[6:7], off
	v_lshl_add_u64 v[4:5], v[4:5], 0, s[6:7]
	s_add_i32 m0, s34, 0x1a000
	s_add_i32 s39, s34, 0x8000
	s_add_i32 s40, s34, 0xa000
	global_load_lds_dwordx4 v[4:5], off
	v_lshl_add_u64 v[0:1], v[0:1], 0, s[6:7]
	s_mov_b32 m0, s39
	s_add_u32 s14, s24, 0x40080
	global_load_lds_dwordx4 v[0:1], off
	v_lshl_add_u64 v[0:1], v[2:3], 0, s[6:7]
	s_mov_b32 m0, s40
	s_addc_u32 s15, s25, 0
	global_load_lds_dwordx4 v[0:1], off
	s_add_i32 m0, s34, 0x1c000
	v_lshl_add_u64 v[0:1], s[14:15], 0, v[132:133]
	global_load_lds_dwordx4 v[0:1], off
	v_lshl_add_u64 v[0:1], s[14:15], 0, v[128:129]
	s_add_i32 m0, s34, 0x1e000
	s_cmpk_lt_u32 s5, 0x100
	global_load_lds_dwordx4 v[0:1], off
	v_lshrrev_b32_e32 v1, 1, v9
	v_and_b32_e32 v1, 24, v1
	v_and_b32_e32 v0, 15, v9
	v_lshlrev_b32_e32 v2, 1, v1
	v_lshl_or_b32 v148, s12, 6, v0
	v_lshl_or_b32 v0, v0, 6, v2
	v_lshlrev_b32_e32 v2, 2, v9
	v_and_b32_e32 v2, 32, v2
	v_bitop3_b32 v3, v0, s13, v2 bitop3:0xde
	v_bitop3_b32 v149, v0, s17, v2 bitop3:0xde
	v_lshlrev_b32_e32 v0, 14, v13
	v_and_b32_e32 v0, 0xffff8000, v0
	v_or_b32_e32 v150, s16, v1
	v_lshl_add_u32 v0, v12, 11, v0
	v_and_b32_e32 v1, 1, v13
	v_lshl_or_b32 v0, v1, 6, v0
	v_lshl_add_u32 v136, v14, 1, v0
	v_lshlrev_b32_e32 v0, 14, v8
	v_and_b32_e32 v0, 0xffff8000, v0
	s_waitcnt vmcnt(0)
	v_lshl_add_u32 v0, v10, 11, v0
	v_and_b32_e32 v1, 1, v8
	s_sext_i32_i8 s1, s4
	s_cselect_b64 s[12:13], -1, 0
	v_readlane_b32 s4, v235, 6
	v_lshl_or_b32 v0, v1, 6, v0
	s_add_i32 s43, 0, 0x10000
	s_add_i32 s44, 0, 0x14000
	s_ashr_i32 s41, s4, 31
	s_mov_b32 s42, s4
	v_mov_b32_e32 v137, v133
	v_lshl_add_u32 v138, v11, 1, v0
	v_mov_b32_e32 v139, v133
	v_mov_b64_e32 v[140:141], 0xb00
	v_mov_b64_e32 v[142:143], 0xaff
	v_add_u32_e32 v151, s43, v149
	v_add_u32_e32 v152, s44, v149
	v_add_u32_e32 v153, 0, v3
	v_mov_b32_e32 v154, 0x358637bd
	s_mov_b32 s45, 0x800000
	s_movk_i32 s46, 0x1600
	s_barrier
	v_readlane_b32 s5, v235, 7
	s_mov_b32 s98, 0
	s_branch .LBB0_779

; __device__ __forceinline__ unsigned pk2(float lo, float hi) { return pg8::cvt_pk_bf16(lo, hi); }
; __device__ __forceinline__ float silu_f(float x) { return x * sigmoid_f(x); }
;     __host__ __device__ bool next(int i, Unit& u) const {
;         const long L = (long)i * G + c; if (L >= nwg) return false;
;         int wgid = (int)L; { const int q = nwg / NXCD, r = nwg % NXCD, xcd = wgid % NXCD, off = wgid / NXCD; wgid = (xcd < r ? xcd * (q + 1) : r * (q + 1) + (xcd - r) * q) + off; }
;         const int nig = WGM * nN, gid = wgid / nig, fm = gid * WGM, gsz = (nM - fm) < WGM ? (nM - fm) : WGM;
;         u.pm = fm + ((wgid % nig) % gsz); u.pn = (wgid % nig) / gsz; return true;
;     }
;     __device__ __forceinline__ void operator()(const f32x4 (&acc)[2][2][4][2], const pg8::Unit& u, int wr, int wc, int fr, int fq) const {
;     ...
;                 const int row = row0 + ai * 128 + m * 16;
;                 const float rs = sumsq ? rsqrtf(sumsq[row] * (1.f / 1024.f) + EPS) : 1.f;
;                 float o[8];
; #pragma unroll
;                 for (int n = 0; n < 2; ++n)
; #pragma unroll
;                     for (int e = 0; e < 4; ++e) { const float g = acc[ai][0][m][n][e] * rs, up = acc[ai][1][m][n][e] * rs; o[4 * n + e] = silu_f(g) * up; }
;                 u32x4 w; w.x = pk2(o[0], o[1]); w.y = pk2(o[2], o[3]); w.z = pk2(o[4], o[5]); w.w = pk2(o[6], o[7]);
;                 *(u32x4*)(H + (size_t)row * DFF + col) = w;
.LBB0_779:
	s_add_i32 s38, s38, 1
	s_mul_i32 s4, s38, s41
	s_mul_hi_u32 s5, s38, s42
	s_add_i32 s5, s5, s4
	s_mul_i32 s4, s38, s42
	v_readlane_b32 s15, v235, 0
	s_add_u32 s18, s4, s15
	s_addc_u32 s19, s5, s31
	v_cmp_gt_i64_e32 vcc, s[18:19], v[142:143]
	v_cmp_lt_i64_e64 s[4:5], s[18:19], v[140:141]
	s_cbranch_vccnz .LBB0_781
	s_ashr_i32 s14, s18, 31
	s_lshr_b32 s14, s14, 29
	s_add_i32 s14, s18, s14
	s_ashr_i32 s15, s14, 3
	s_and_b32 s14, s14, -8
	s_sub_i32 s14, s18, s14
	s_cmp_lt_i32 s14, 0
	s_cselect_b32 s16, s33, 0x160
	s_mul_i32 s14, s14, s16
	s_add_i32 s14, s14, s15
	s_mul_hi_i32 s15, s14, 0x2e8ba2e9
	s_lshr_b32 s16, s15, 31
	s_ashr_i32 s15, s15, 4
	s_add_i32 s15, s15, s16
	s_lshl_b32 s16, s15, 2
	s_sub_i32 s17, 0x80, s16
	s_min_i32 s17, s17, 4
	s_abs_i32 s18, s17
	v_cvt_f32_u32_e32 v230, s18
	s_sub_i32 s20, 0, s18
	s_mulk_i32 s15, 0x58
	s_sub_i32 s15, s14, s15
	v_rcp_iflag_f32_e32 v230, v230
	s_abs_i32 s14, s15
	s_xor_b32 s19, s15, s17
	s_ashr_i32 s19, s19, 31
	v_mul_f32_e32 v230, 0x4f7ffffe, v230
	v_cvt_u32_f32_e32 v230, v230
	s_nop 0
	v_readfirstlane_b32 s21, v230
	s_mul_i32 s20, s20, s21
	s_mul_hi_u32 s20, s21, s20
	s_add_i32 s21, s21, s20
	s_mul_hi_u32 s20, s14, s21
	s_mul_i32 s21, s20, s18
	s_sub_i32 s14, s14, s21
	s_add_i32 s26, s20, 1
	s_sub_i32 s21, s14, s18
	s_cmp_ge_u32 s14, s18
	s_cselect_b32 s20, s26, s20
	s_cselect_b32 s14, s21, s14
	s_add_i32 s21, s20, 1
	s_cmp_ge_u32 s14, s18
	s_cselect_b32 s14, s21, s20
	s_xor_b32 s14, s14, s19
	s_sub_i32 s14, s14, s19
	s_mul_i32 s17, s14, s17
	s_sub_i32 s15, s15, s17
	s_add_i32 s16, s16, s15
.LBB0_781:
	s_ashr_i32 s17, s16, 31
	s_lshl_b64 s[18:19], s[16:17], 19
	s_add_u32 s18, s8, s18
	s_addc_u32 s19, s9, s19
	s_and_b64 s[20:21], s[4:5], exec
	s_cselect_b32 s17, s19, s23
	s_cselect_b32 s47, s18, s22
	s_ashr_i32 s15, s14, 31
	s_lshl_b64 s[20:21], s[14:15], 19
	s_add_u32 s20, s28, s20
	s_addc_u32 s21, s29, s21
	s_and_b64 s[26:27], s[4:5], exec
	s_cselect_b32 s15, s21, s25
	s_cselect_b32 s48, s20, s24
	s_add_u32 s22, s22, 0x40080
	s_addc_u32 s23, s23, 0
	s_add_u32 s49, s24, 0x100
	s_addc_u32 s50, s25, 0
	s_mov_b32 s51, -2
	s_cmp_eq_u32 s98, 0
	s_cbranch_scc1 .Lp6_plain
	ds_read_b128 v[144:147], v151
	ds_read_b128 v[156:159], v151 offset:1024
	ds_read_b128 v[160:163], v151 offset:2048
	ds_read_b128 v[164:167], v151 offset:3072
	ds_read_b128 v[168:171], v152
	ds_read_b128 v[172:175], v152 offset:1024
	ds_read_b128 v[176:179], v152 offset:2048
	ds_read_b128 v[180:183], v152 offset:3072
	s_add_u32 s24, s22, 0xfffc0080
	s_addc_u32 s25, s23, -1
	s_cmp_eq_u32 s51, 12
	s_cselect_b32 s27, s17, s25
	s_cselect_b32 s26, s47, s24
	s_cselect_b32 s25, s15, s50
	s_cselect_b32 s24, s48, s49
	v_lshl_add_u64 v[218:219], s[22:23], 0, v[136:137]
	s_add_i32 m0, s34, 0xc000
	ds_read_b128 v[184:187], v153
	ds_read_b128 v[190:193], v153 offset:1024
	ds_read_b128 v[194:197], v153 offset:2048
	ds_read_b128 v[198:201], v153 offset:3072
	ds_read_b128 v[202:205], v153 offset:4096
	ds_read_b128 v[206:209], v153 offset:5120
	ds_read_b128 v[210:213], v153 offset:6144
	ds_read_b128 v[214:217], v153 offset:7168
	global_load_lds_dwordx4 v[218:219], off
	v_lshl_add_u64 v[218:219], s[22:23], 0, v[138:139]
	s_add_i32 m0, s34, 0xe000
	s_nop 0
	global_load_lds_dwordx4 v[218:219], off
	s_nop 0
	s_nop 0
	v_mov_b32_e32 v65, v56
	v_mov_b32_e32 v56, v61
	v_mov_b32_e32 v61, v58
	v_mov_b32_e32 v58, v63
	v_mov_b32_e32 v63, v48
	v_mov_b32_e32 v48, v53
	v_mov_b32_e32 v53, v50
	v_mov_b32_e32 v50, v55
	v_mov_b32_e32 v64, v60
	v_mov_b32_e32 v60, v62
	v_mov_b32_e32 v62, v52
	v_mov_b32_e32 v52, v54
	v_add_u32_e32 v54, 0x80, v228
	s_nop 0
	v_fmamk_f32 v55, v239, 0x3a800000, v154
	v_mul_f32_e32 v66, 0x4b800000, v55
	v_cmp_gt_f32_e32 vcc, s45, v55
	s_nop 1
	v_cndmask_b32_e32 v55, v55, v66, vcc
	v_rsq_f32_e32 v66, v55
	v_mad_i64_i32 v[54:55], s[100:101], v54, s46, v[120:121]
	v_lshl_add_u64 v[54:55], v[54:55], 0, v[122:123]
	v_mul_f32_e32 v67, 0x45800000, v66
	v_cndmask_b32_e32 v66, v66, v67, vcc
	v_pk_mul_f32 v[50:51], v[50:51], v[66:67] op_sel_hi:[1,0]
	v_pk_mul_f32 v[64:65], v[64:65], v[66:67] op_sel_hi:[1,0]
	v_pk_mul_f32 v[56:57], v[56:57], v[66:67] op_sel_hi:[1,0]
	v_pk_mul_f32 v[60:61], v[60:61], v[66:67] op_sel_hi:[1,0]
	v_pk_mul_f32 v[58:59], v[58:59], v[66:67] op_sel_hi:[1,0]
	v_pk_mul_f32 v[62:63], v[62:63], v[66:67] op_sel_hi:[1,0]
	v_pk_mul_f32 v[48:49], v[48:49], v[66:67] op_sel_hi:[1,0]
	v_pk_mul_f32 v[52:53], v[52:53], v[66:67] op_sel_hi:[1,0]
	v_mul_f32_e32 v73, 0xbfb8aa3b, v51
	v_mul_f32_e32 v66, 0xbfb8aa3b, v65
	v_mul_f32_e32 v67, 0xbfb8aa3b, v57
	v_mul_f32_e32 v68, 0xbfb8aa3b, v61
	v_mul_f32_e32 v69, 0xbfb8aa3b, v59
	v_mul_f32_e32 v70, 0xbfb8aa3b, v63
	v_mul_f32_e32 v71, 0xbfb8aa3b, v49
	v_mul_f32_e32 v72, 0xbfb8aa3b, v53
	v_exp_f32_e32 v73, v73
	v_exp_f32_e32 v66, v66
	v_exp_f32_e32 v67, v67
	v_exp_f32_e32 v68, v68
	v_exp_f32_e32 v69, v69
	v_exp_f32_e32 v70, v70
	v_exp_f32_e32 v71, v71
	v_exp_f32_e32 v72, v72
	v_add_f32_e32 v73, 1.0, v73
	v_add_f32_e32 v66, 1.0, v66
	v_add_f32_e32 v67, 1.0, v67
	v_add_f32_e32 v68, 1.0, v68
	v_add_f32_e32 v69, 1.0, v69
	v_add_f32_e32 v70, 1.0, v70
	v_add_f32_e32 v71, 1.0, v71
	v_add_f32_e32 v72, 1.0, v72
	v_rcp_f32_e32 v73, v73
	v_rcp_f32_e32 v66, v66
	v_rcp_f32_e32 v67, v67
	v_rcp_f32_e32 v68, v68
	v_rcp_f32_e32 v69, v69
	v_rcp_f32_e32 v70, v70
	v_rcp_f32_e32 v71, v71
	v_rcp_f32_e32 v72, v72
	v_mul_f32_e32 v51, v51, v73
	v_mul_f32_e32 v65, v65, v66
	v_mul_f32_e32 v57, v57, v67
	v_mul_f32_e32 v61, v61, v68
	v_mul_f32_e32 v59, v59, v69
	v_mul_f32_e32 v63, v63, v70
	v_mul_f32_e32 v49, v49, v71
	v_mul_f32_e32 v53, v53, v72
	v_mul_f32_e32 v51, v50, v51
	v_mul_f32_e32 v64, v64, v65
; __device__ __forceinline__ unsigned pk2(float lo, float hi) { return pg8::cvt_pk_bf16(lo, hi); }
; __device__ __forceinline__ float silu_f(float x) { return x * sigmoid_f(x); }
;     __device__ __forceinline__ void operator()(const f32x4 (&acc)[2][2][4][2], const pg8::Unit& u, int wr, int wc, int fr, int fq) const {
;     ...
;                 const int row = row0 + ai * 128 + m * 16;
;                 const float rs = sumsq ? rsqrtf(sumsq[row] * (1.f / 1024.f) + EPS) : 1.f;
;                 float o[8];
; #pragma unroll
;                 for (int n = 0; n < 2; ++n)
; #pragma unroll
;                     for (int e = 0; e < 4; ++e) { const float g = acc[ai][0][m][n][e] * rs, up = acc[ai][1][m][n][e] * rs; o[4 * n + e] = silu_f(g) * up; }
;                 u32x4 w; w.x = pk2(o[0], o[1]); w.y = pk2(o[2], o[3]); w.z = pk2(o[4], o[5]); w.w = pk2(o[6], o[7]);
;                 *(u32x4*)(H + (size_t)row * DFF + col) = w;
	v_mul_f32_e32 v56, v56, v57
	v_mul_f32_e32 v57, v60, v61
	v_mul_f32_e32 v58, v58, v59
	v_mul_f32_e32 v59, v62, v63
	v_mul_f32_e32 v60, v48, v49
	v_mul_f32_e32 v52, v52, v53
	v_cvt_pk_bf16_f32 v48, v64, v56
	v_cvt_pk_bf16_f32 v49, v57, v58
	v_cvt_pk_bf16_f32 v50, v59, v60
	v_cvt_pk_bf16_f32 v51, v52, v51
	global_store_dwordx4 v[54:55], v[48:51], off
	s_nop 0
	s_nop 0
	v_mov_b32_e32 v49, v40
	v_mov_b32_e32 v40, v45
	v_mov_b32_e32 v45, v42
	v_mov_b32_e32 v42, v47
	v_mov_b32_e32 v47, v32
	v_mov_b32_e32 v32, v37
	v_mov_b32_e32 v37, v34
	v_mov_b32_e32 v34, v39
	v_mov_b32_e32 v48, v44
	v_mov_b32_e32 v44, v46
	v_mov_b32_e32 v46, v36
	v_mov_b32_e32 v36, v38
	v_add_u32_e32 v38, 0x90, v228
	s_nop 0
	v_fmamk_f32 v39, v240, 0x3a800000, v154
	v_mul_f32_e32 v50, 0x4b800000, v39
	v_cmp_gt_f32_e32 vcc, s45, v39
	s_nop 1
	v_cndmask_b32_e32 v39, v39, v50, vcc
	v_rsq_f32_e32 v50, v39
	v_mad_i64_i32 v[38:39], s[100:101], v38, s46, v[120:121]
	v_lshl_add_u64 v[38:39], v[38:39], 0, v[122:123]
	v_mul_f32_e32 v51, 0x45800000, v50
	v_cndmask_b32_e32 v50, v50, v51, vcc
	v_pk_mul_f32 v[34:35], v[34:35], v[50:51] op_sel_hi:[1,0]
	v_pk_mul_f32 v[48:49], v[48:49], v[50:51] op_sel_hi:[1,0]
	v_pk_mul_f32 v[40:41], v[40:41], v[50:51] op_sel_hi:[1,0]
	v_pk_mul_f32 v[44:45], v[44:45], v[50:51] op_sel_hi:[1,0]
	v_pk_mul_f32 v[42:43], v[42:43], v[50:51] op_sel_hi:[1,0]
	v_pk_mul_f32 v[46:47], v[46:47], v[50:51] op_sel_hi:[1,0]
	v_pk_mul_f32 v[32:33], v[32:33], v[50:51] op_sel_hi:[1,0]
	v_pk_mul_f32 v[36:37], v[36:37], v[50:51] op_sel_hi:[1,0]
	v_mul_f32_e32 v57, 0xbfb8aa3b, v35
	v_mul_f32_e32 v50, 0xbfb8aa3b, v49
	v_mul_f32_e32 v51, 0xbfb8aa3b, v41
	v_mul_f32_e32 v52, 0xbfb8aa3b, v45
	v_mul_f32_e32 v53, 0xbfb8aa3b, v43
	v_mul_f32_e32 v54, 0xbfb8aa3b, v47
	v_mul_f32_e32 v55, 0xbfb8aa3b, v33
	v_mul_f32_e32 v56, 0xbfb8aa3b, v37
	v_exp_f32_e32 v57, v57
	v_exp_f32_e32 v50, v50
	v_exp_f32_e32 v51, v51
	v_exp_f32_e32 v52, v52
	v_exp_f32_e32 v53, v53
	v_exp_f32_e32 v54, v54
	v_exp_f32_e32 v55, v55
	v_exp_f32_e32 v56, v56
	v_add_f32_e32 v57, 1.0, v57
	v_add_f32_e32 v50, 1.0, v50
	v_add_f32_e32 v51, 1.0, v51
	v_add_f32_e32 v52, 1.0, v52
	v_add_f32_e32 v53, 1.0, v53
	v_add_f32_e32 v54, 1.0, v54
	v_add_f32_e32 v55, 1.0, v55
	v_add_f32_e32 v56, 1.0, v56
	v_rcp_f32_e32 v57, v57
	v_rcp_f32_e32 v50, v50
	v_rcp_f32_e32 v51, v51
	v_rcp_f32_e32 v52, v52
	v_rcp_f32_e32 v53, v53
	v_rcp_f32_e32 v54, v54
	v_rcp_f32_e32 v55, v55
	v_rcp_f32_e32 v56, v56
	v_mul_f32_e32 v35, v35, v57
	v_mul_f32_e32 v49, v49, v50
	v_mul_f32_e32 v41, v41, v51
	v_mul_f32_e32 v45, v45, v52
	v_mul_f32_e32 v43, v43, v53
	v_mul_f32_e32 v47, v47, v54
	v_mul_f32_e32 v33, v33, v55
	v_mul_f32_e32 v37, v37, v56
	v_mul_f32_e32 v35, v34, v35
	v_mul_f32_e32 v48, v48, v49
	v_mul_f32_e32 v40, v40, v41
	v_mul_f32_e32 v41, v44, v45
	v_mul_f32_e32 v42, v42, v43
	v_mul_f32_e32 v43, v46, v47
	v_mul_f32_e32 v44, v32, v33
	v_mul_f32_e32 v36, v36, v37
	v_cvt_pk_bf16_f32 v32, v48, v40
	v_cvt_pk_bf16_f32 v33, v41, v42
	v_cvt_pk_bf16_f32 v34, v43, v44
	v_cvt_pk_bf16_f32 v35, v36, v35
	global_store_dwordx4 v[38:39], v[32:35], off
	s_nop 0
	s_nop 0
	v_mov_b32_e32 v33, v24
	v_mov_b32_e32 v24, v29
	v_mov_b32_e32 v29, v26
	v_mov_b32_e32 v26, v31
	v_mov_b32_e32 v31, v16
	v_mov_b32_e32 v16, v21
	v_mov_b32_e32 v21, v18
	v_mov_b32_e32 v18, v23
	v_mov_b32_e32 v32, v28
	v_mov_b32_e32 v28, v30
	v_mov_b32_e32 v30, v20
	v_mov_b32_e32 v20, v22
	v_add_u32_e32 v22, 0xa0, v228
	s_nop 0
	v_fmamk_f32 v23, v241, 0x3a800000, v154
	v_mul_f32_e32 v34, 0x4b800000, v23
	v_cmp_gt_f32_e32 vcc, s45, v23
	s_nop 1
	v_cndmask_b32_e32 v23, v23, v34, vcc
	v_rsq_f32_e32 v34, v23
	v_mad_i64_i32 v[22:23], s[100:101], v22, s46, v[120:121]
	v_lshl_add_u64 v[22:23], v[22:23], 0, v[122:123]
	v_mul_f32_e32 v35, 0x45800000, v34
	v_cndmask_b32_e32 v34, v34, v35, vcc
	v_pk_mul_f32 v[18:19], v[18:19], v[34:35] op_sel_hi:[1,0]
	v_pk_mul_f32 v[32:33], v[32:33], v[34:35] op_sel_hi:[1,0]
	v_pk_mul_f32 v[24:25], v[24:25], v[34:35] op_sel_hi:[1,0]
	v_pk_mul_f32 v[28:29], v[28:29], v[34:35] op_sel_hi:[1,0]
	v_pk_mul_f32 v[26:27], v[26:27], v[34:35] op_sel_hi:[1,0]
	v_pk_mul_f32 v[30:31], v[30:31], v[34:35] op_sel_hi:[1,0]
	v_pk_mul_f32 v[16:17], v[16:17], v[34:35] op_sel_hi:[1,0]
	v_pk_mul_f32 v[20:21], v[20:21], v[34:35] op_sel_hi:[1,0]
	v_mul_f32_e32 v41, 0xbfb8aa3b, v19
	v_mul_f32_e32 v34, 0xbfb8aa3b, v33
	v_mul_f32_e32 v35, 0xbfb8aa3b, v25
	v_mul_f32_e32 v36, 0xbfb8aa3b, v29
	v_mul_f32_e32 v37, 0xbfb8aa3b, v27
	v_mul_f32_e32 v38, 0xbfb8aa3b, v31
	v_mul_f32_e32 v39, 0xbfb8aa3b, v17
	v_mul_f32_e32 v40, 0xbfb8aa3b, v21
	v_exp_f32_e32 v41, v41
	v_exp_f32_e32 v34, v34
	v_exp_f32_e32 v35, v35
	v_exp_f32_e32 v36, v36
	v_exp_f32_e32 v37, v37
	v_exp_f32_e32 v38, v38
	v_exp_f32_e32 v39, v39
	v_exp_f32_e32 v40, v40
	v_add_f32_e32 v41, 1.0, v41
	v_add_f32_e32 v34, 1.0, v34
	v_add_f32_e32 v35, 1.0, v35
	v_add_f32_e32 v36, 1.0, v36
	v_add_f32_e32 v37, 1.0, v37
	v_add_f32_e32 v38, 1.0, v38
	v_add_f32_e32 v39, 1.0, v39
	v_add_f32_e32 v40, 1.0, v40
	v_rcp_f32_e32 v41, v41
	v_rcp_f32_e32 v34, v34
	v_rcp_f32_e32 v35, v35
	v_rcp_f32_e32 v36, v36
	v_rcp_f32_e32 v37, v37
	v_rcp_f32_e32 v38, v38
	v_rcp_f32_e32 v39, v39
	v_rcp_f32_e32 v40, v40
	v_mul_f32_e32 v19, v19, v41
	v_mul_f32_e32 v33, v33, v34
	v_mul_f32_e32 v25, v25, v35
	v_mul_f32_e32 v29, v29, v36
	v_mul_f32_e32 v27, v27, v37
	v_mul_f32_e32 v31, v31, v38
	v_mul_f32_e32 v17, v17, v39
	v_mul_f32_e32 v21, v21, v40
	v_mul_f32_e32 v19, v18, v19
	v_mul_f32_e32 v32, v32, v33
	v_mul_f32_e32 v24, v24, v25
	v_mul_f32_e32 v25, v28, v29
	v_mul_f32_e32 v26, v26, v27
	v_mul_f32_e32 v27, v30, v31
	v_mul_f32_e32 v28, v16, v17
	v_mul_f32_e32 v20, v20, v21
; #define PG8_STAGE(bufoff, gbase, voff) do { _Pragma("unroll") for (int _i = 0; _i < 2; ++_i) \
;         __builtin_amdgcn_global_load_lds((const unsigned*)((const char*)(gbase) + (voff)[_i]), (PG8_LAS unsigned*)(lds + (bufoff) + ldsw + _i * 8192), 16, 0, 0); } while (0)
; #define PG8_LDA(dst, b, h) do { _Pragma("unroll") for (int m = 0; m < 4; ++m) _Pragma("unroll") for (int k = 0; k < 2; ++k) dst[m][k] = *(const PG8_LAS bf16x8*)(lds + PG8_SA(b, h) + aoff + m * 2048 + k * 1024); } while (0)
; #define PG8_LDB(dst, b, h) do { _Pragma("unroll") for (int n = 0; n < 2; ++n) _Pragma("unroll") for (int k = 0; k < 2; ++k) dst[n][k] = *(const PG8_LAS bf16x8*)(lds + PG8_SB(b, h) + boff + n * 2048 + k * 1024); } while (0)
; #define PG8_MMA(ai, bj, At, Bt) do { __builtin_amdgcn_s_setprio(1); _Pragma("unroll") for (int m = 0; m < 4; ++m) _Pragma("unroll") for (int n = 0; n < 2; ++n) _Pragma("unroll") for (int k = 0; k < 2; ++k) \
;         acc[ai][bj][m][n] = __builtin_amdgcn_mfma_f32_16x16x32_bf16(Bt[n][k], At[m][k], acc[ai][bj][m][n], 0, 0, 0); __builtin_amdgcn_s_setprio(0); } while (0)
; #define PG8_WAIT_V(n) asm volatile("s_waitcnt vmcnt(" #n ")" ::: "memory")
; template <class Epi, class Sched, bool ALIGN_EPI = false, bool SP2 = false>
; __device__ __forceinline__ void gemm_phase(PG8_LAS unsigned char* lds, const Gemm g, const Sched& S, const Epi& E) {
;     ...
;             PG8_LDB(B0, 0, 0); PG8_LDB(B1, 0, 1); PG8_SCHED; PG8_LDA(At, 0, 0); PG8_STAGE(PG8_SA(1, 1), a1 + hstep, voffA);
;             PG8_WAIT_V(8); PG8_WAIT_L(0); PG8_BAR; PG8_MMA(0, 0, At, B0); PG8_MMA(0, 1, At, B1); PG8_BAR; PG8_SCHED;
;     __device__ __forceinline__ void operator()(const f32x4 (&acc)[2][2][4][2], const pg8::Unit& u, int wr, int wc, int fr, int fq) const {
;     ...
;                 const int row = row0 + ai * 128 + m * 16;
;                 const float rs = sumsq ? rsqrtf(sumsq[row] * (1.f / 1024.f) + EPS) : 1.f;
;                 float o[8];
; #pragma unroll
;                 for (int n = 0; n < 2; ++n)
; #pragma unroll
;                     for (int e = 0; e < 4; ++e) { const float g = acc[ai][0][m][n][e] * rs, up = acc[ai][1][m][n][e] * rs; o[4 * n + e] = silu_f(g) * up; }
;                 u32x4 w; w.x = pk2(o[0], o[1]); w.y = pk2(o[2], o[3]); w.z = pk2(o[4], o[5]); w.w = pk2(o[6], o[7]);
;                 *(u32x4*)(H + (size_t)row * DFF + col) = w;
	v_cvt_pk_bf16_f32 v16, v32, v24
	v_cvt_pk_bf16_f32 v17, v25, v26
	v_cvt_pk_bf16_f32 v18, v27, v28
	v_cvt_pk_bf16_f32 v19, v20, v19
	global_store_dwordx4 v[22:23], v[16:19], off
	s_nop 0
	v_mov_b32_e32 v17, v8
	v_mov_b32_e32 v8, v13
	v_mov_b32_e32 v13, v10
	v_mov_b32_e32 v10, v15
	v_mov_b32_e32 v15, v0
	v_mov_b32_e32 v0, v5
	v_mov_b32_e32 v5, v2
	v_mov_b32_e32 v2, v7
	v_mov_b32_e32 v16, v12
	v_mov_b32_e32 v12, v14
	v_mov_b32_e32 v14, v4
	v_mov_b32_e32 v4, v6
	v_add_u32_e32 v6, 0xb0, v228
	s_nop 0
	v_fmamk_f32 v7, v242, 0x3a800000, v154
	v_mul_f32_e32 v18, 0x4b800000, v7
	v_cmp_gt_f32_e64 vcc, s45, v7
	s_nop 1
	v_cndmask_b32_e64 v7, v7, v18, vcc
	v_rsq_f32_e32 v18, v7
	v_mad_i64_i32 v[6:7], s[100:101], v6, s46, v[120:121]
	v_lshl_add_u64 v[6:7], v[6:7], 0, v[122:123]
	v_mul_f32_e32 v19, 0x45800000, v18
	v_cndmask_b32_e64 v18, v18, v19, vcc
	v_pk_mul_f32 v[2:3], v[2:3], v[18:19] op_sel_hi:[1,0]
	v_pk_mul_f32 v[16:17], v[16:17], v[18:19] op_sel_hi:[1,0]
	v_pk_mul_f32 v[8:9], v[8:9], v[18:19] op_sel_hi:[1,0]
	v_pk_mul_f32 v[12:13], v[12:13], v[18:19] op_sel_hi:[1,0]
	v_pk_mul_f32 v[10:11], v[10:11], v[18:19] op_sel_hi:[1,0]
	v_pk_mul_f32 v[14:15], v[14:15], v[18:19] op_sel_hi:[1,0]
	v_pk_mul_f32 v[0:1], v[0:1], v[18:19] op_sel_hi:[1,0]
	v_pk_mul_f32 v[4:5], v[4:5], v[18:19] op_sel_hi:[1,0]
	v_mul_f32_e32 v25, 0xbfb8aa3b, v3
	v_mul_f32_e32 v18, 0xbfb8aa3b, v17
	v_mul_f32_e32 v19, 0xbfb8aa3b, v9
	v_mul_f32_e32 v20, 0xbfb8aa3b, v13
	v_mul_f32_e32 v21, 0xbfb8aa3b, v11
	v_mul_f32_e32 v22, 0xbfb8aa3b, v15
	v_mul_f32_e32 v23, 0xbfb8aa3b, v1
	v_mul_f32_e32 v24, 0xbfb8aa3b, v5
	v_exp_f32_e32 v25, v25
	v_exp_f32_e32 v18, v18
	v_exp_f32_e32 v19, v19
	v_exp_f32_e32 v20, v20
	v_exp_f32_e32 v21, v21
	v_exp_f32_e32 v22, v22
	v_exp_f32_e32 v23, v23
	v_exp_f32_e32 v24, v24
	v_add_f32_e32 v25, 1.0, v25
	v_add_f32_e32 v18, 1.0, v18
	v_add_f32_e32 v19, 1.0, v19
	v_add_f32_e32 v20, 1.0, v20
	v_add_f32_e32 v21, 1.0, v21
	v_add_f32_e32 v22, 1.0, v22
	v_add_f32_e32 v23, 1.0, v23
	v_add_f32_e32 v24, 1.0, v24
	v_rcp_f32_e32 v25, v25
	v_rcp_f32_e32 v18, v18
	v_rcp_f32_e32 v19, v19
	v_rcp_f32_e32 v20, v20
	v_rcp_f32_e32 v21, v21
	v_rcp_f32_e32 v22, v22
	v_rcp_f32_e32 v23, v23
	v_rcp_f32_e32 v24, v24
	v_mul_f32_e32 v3, v3, v25
	v_mul_f32_e32 v17, v17, v18
	v_mul_f32_e32 v9, v9, v19
	v_mul_f32_e32 v13, v13, v20
	v_mul_f32_e32 v11, v11, v21
	v_mul_f32_e32 v15, v15, v22
	v_mul_f32_e32 v1, v1, v23
	v_mul_f32_e32 v5, v5, v24
	v_mul_f32_e32 v3, v2, v3
	v_mul_f32_e32 v16, v16, v17
	v_mul_f32_e32 v8, v8, v9
	v_mul_f32_e32 v9, v12, v13
	v_mul_f32_e32 v10, v10, v11
	v_mul_f32_e32 v11, v14, v15
	v_mul_f32_e32 v12, v0, v1
	v_mul_f32_e32 v4, v4, v5
	v_cvt_pk_bf16_f32 v0, v16, v8
	v_cvt_pk_bf16_f32 v1, v9, v10
	v_cvt_pk_bf16_f32 v2, v11, v12
	v_cvt_pk_bf16_f32 v3, v4, v3
	global_store_dwordx4 v[6:7], v[0:3], off
	s_waitcnt vmcnt(16)
	s_waitcnt lgkmcnt(0)
	s_barrier
	s_setprio 1
	v_mfma_f32_16x16x32_bf16 v[116:119], v[144:147], v[184:187], 0
	v_mfma_f32_16x16x32_bf16 v[112:115], v[160:163], v[184:187], 0
	v_mfma_f32_16x16x32_bf16 v[100:103], v[144:147], v[194:197], 0
	v_mfma_f32_16x16x32_bf16 v[96:99], v[160:163], v[194:197], 0
	v_mfma_f32_16x16x32_bf16 v[84:87], v[144:147], v[202:205], 0
	v_mfma_f32_16x16x32_bf16 v[80:83], v[160:163], v[202:205], 0
	v_mfma_f32_16x16x32_bf16 v[72:75], v[144:147], v[210:213], 0
	v_mfma_f32_16x16x32_bf16 v[64:67], v[160:163], v[210:213], 0
	v_mfma_f32_16x16x32_bf16 v[116:119], v[156:159], v[190:193], v[116:119]
	v_mfma_f32_16x16x32_bf16 v[112:115], v[164:167], v[190:193], v[112:115]
	v_mfma_f32_16x16x32_bf16 v[100:103], v[156:159], v[198:201], v[100:103]
	v_mfma_f32_16x16x32_bf16 v[96:99], v[164:167], v[198:201], v[96:99]
	v_mfma_f32_16x16x32_bf16 v[84:87], v[156:159], v[206:209], v[84:87]
	v_mfma_f32_16x16x32_bf16 v[80:83], v[164:167], v[206:209], v[80:83]
	v_mfma_f32_16x16x32_bf16 v[72:75], v[156:159], v[214:217], v[72:75]
	v_mfma_f32_16x16x32_bf16 v[64:67], v[164:167], v[214:217], v[64:67]
	v_mfma_f32_16x16x32_bf16 v[124:127], v[168:171], v[184:187], 0
	v_mfma_f32_16x16x32_bf16 v[120:123], v[176:179], v[184:187], 0
	v_mfma_f32_16x16x32_bf16 v[108:111], v[168:171], v[194:197], 0
	v_mfma_f32_16x16x32_bf16 v[104:107], v[176:179], v[194:197], 0
	v_mfma_f32_16x16x32_bf16 v[92:95], v[168:171], v[202:205], 0
	v_mfma_f32_16x16x32_bf16 v[88:91], v[176:179], v[202:205], 0
	v_mfma_f32_16x16x32_bf16 v[76:79], v[168:171], v[210:213], 0
	v_mfma_f32_16x16x32_bf16 v[68:71], v[176:179], v[210:213], 0
	v_mfma_f32_16x16x32_bf16 v[124:127], v[172:175], v[190:193], v[124:127]
	v_mfma_f32_16x16x32_bf16 v[120:123], v[180:183], v[190:193], v[120:123]
	v_mfma_f32_16x16x32_bf16 v[108:111], v[172:175], v[198:201], v[108:111]
	v_mfma_f32_16x16x32_bf16 v[104:107], v[180:183], v[198:201], v[104:107]
	v_mfma_f32_16x16x32_bf16 v[92:95], v[172:175], v[206:209], v[92:95]
	v_mfma_f32_16x16x32_bf16 v[88:91], v[180:183], v[206:209], v[88:91]
	v_mfma_f32_16x16x32_bf16 v[76:79], v[172:175], v[214:217], v[76:79]
	v_mfma_f32_16x16x32_bf16 v[68:71], v[180:183], v[214:217], v[68:71]
	s_setprio 0
	s_barrier
; #define PG8_STAGE(bufoff, gbase, voff) do { _Pragma("unroll") for (int _i = 0; _i < 2; ++_i) \
;         __builtin_amdgcn_global_load_lds((const unsigned*)((const char*)(gbase) + (voff)[_i]), (PG8_LAS unsigned*)(lds + (bufoff) + ldsw + _i * 8192), 16, 0, 0); } while (0)
; #define PG8_LDA(dst, b, h) do { _Pragma("unroll") for (int m = 0; m < 4; ++m) _Pragma("unroll") for (int k = 0; k < 2; ++k) dst[m][k] = *(const PG8_LAS bf16x8*)(lds + PG8_SA(b, h) + aoff + m * 2048 + k * 1024); } while (0)
; #define PG8_LDB(dst, b, h) do { _Pragma("unroll") for (int n = 0; n < 2; ++n) _Pragma("unroll") for (int k = 0; k < 2; ++k) dst[n][k] = *(const PG8_LAS bf16x8*)(lds + PG8_SB(b, h) + boff + n * 2048 + k * 1024); } while (0)
; #define PG8_MMA(ai, bj, At, Bt) do { __builtin_amdgcn_s_setprio(1); _Pragma("unroll") for (int m = 0; m < 4; ++m) _Pragma("unroll") for (int n = 0; n < 2; ++n) _Pragma("unroll") for (int k = 0; k < 2; ++k) \
;         acc[ai][bj][m][n] = __builtin_amdgcn_mfma_f32_16x16x32_bf16(Bt[n][k], At[m][k], acc[ai][bj][m][n], 0, 0, 0); __builtin_amdgcn_s_setprio(0); } while (0)
; #define PG8_WAIT_V(n) asm volatile("s_waitcnt vmcnt(" #n ")" ::: "memory")
; #define PG8_WAIT_L(n) asm volatile("s_waitcnt lgkmcnt(" #n ")" ::: "memory")
; #define PG8_BAR __builtin_amdgcn_s_barrier()
; #define PG8_SCHED __builtin_amdgcn_sched_barrier(0)
; template <class Epi, class Sched, bool ALIGN_EPI = false, bool SP2 = false>
; __device__ __forceinline__ void gemm_phase(PG8_LAS unsigned char* lds, const Gemm g, const Sched& S, const Epi& E) {
;     ...
;             PG8_LDA(At, 0, 1); PG8_STAGE(PG8_SB(0, 0), b2, voffB); PG8_STAGE(PG8_SB(0, 1), b2 + hstep, voffB); PG8_STAGE(PG8_SA(0, 0), a2, voffA);
;             PG8_WAIT_V(8); PG8_WAIT_L(0); PG8_BAR; PG8_MMA(1, 0, At, B0); PG8_MMA(1, 1, At, B1); PG8_BAR; PG8_SCHED;
;             PG8_LDB(B0, 1, 0); PG8_LDB(B1, 1, 1); PG8_SCHED; PG8_LDA(At, 1, 0); PG8_STAGE(PG8_SA(0, 1), a2 + hstep, voffA);
;             PG8_WAIT_V(8); PG8_WAIT_L(0); PG8_BAR; PG8_MMA(0, 0, At, B0); PG8_MMA(0, 1, At, B1); PG8_BAR; PG8_SCHED;
	s_add_i32 s52, s43, s30
	v_lshl_add_u64 v[218:219], s[24:25], 0, v[132:133]
	s_mov_b32 m0, s52
	ds_read_b128 v[184:187], v153 offset:16384
	ds_read_b128 v[190:193], v153 offset:17408
	ds_read_b128 v[194:197], v153 offset:18432
	ds_read_b128 v[198:201], v153 offset:19456
	ds_read_b128 v[202:205], v153 offset:20480
	ds_read_b128 v[206:209], v153 offset:21504
	ds_read_b128 v[210:213], v153 offset:22528
	ds_read_b128 v[214:217], v153 offset:23552
	global_load_lds_dwordx4 v[218:219], off
	s_add_i32 m0, s52, 0x2000
	s_add_u32 s52, s24, 0x40000
	v_lshl_add_u64 v[220:221], s[24:25], 0, v[128:129]
	s_addc_u32 s53, s25, 0
	s_add_i32 s54, s44, s30
	global_load_lds_dwordx4 v[220:221], off
	v_lshl_add_u64 v[222:223], s[52:53], 0, v[132:133]
	s_mov_b32 m0, s54
	v_lshl_add_u64 v[224:225], s[26:27], 0, v[130:131]
	global_load_lds_dwordx4 v[222:223], off
	v_lshl_add_u64 v[222:223], s[52:53], 0, v[128:129]
	s_add_i32 m0, s54, 0x2000
	s_nop 0
	global_load_lds_dwordx4 v[222:223], off
	v_lshl_add_u64 v[222:223], s[26:27], 0, v[134:135]
	s_mov_b32 m0, s34
	s_nop 0
	global_load_lds_dwordx4 v[222:223], off
	s_mov_b32 m0, s35
	s_nop 0
	global_load_lds_dwordx4 v[224:225], off
	s_waitcnt vmcnt(16)
	s_waitcnt lgkmcnt(0)
	s_barrier
	s_setprio 1
	v_mfma_f32_16x16x32_bf16 v[56:59], v[144:147], v[184:187], 0
	v_mfma_f32_16x16x32_bf16 v[48:51], v[160:163], v[184:187], 0
	v_mfma_f32_16x16x32_bf16 v[40:43], v[144:147], v[194:197], 0
	v_mfma_f32_16x16x32_bf16 v[32:35], v[160:163], v[194:197], 0
	v_mfma_f32_16x16x32_bf16 v[24:27], v[144:147], v[202:205], 0
	v_mfma_f32_16x16x32_bf16 v[16:19], v[160:163], v[202:205], 0
	v_mfma_f32_16x16x32_bf16 v[8:11], v[144:147], v[210:213], 0
	v_mfma_f32_16x16x32_bf16 v[0:3], v[160:163], v[210:213], 0
	v_mfma_f32_16x16x32_bf16 v[56:59], v[156:159], v[190:193], v[56:59]
	v_mfma_f32_16x16x32_bf16 v[48:51], v[164:167], v[190:193], v[48:51]
	v_mfma_f32_16x16x32_bf16 v[40:43], v[156:159], v[198:201], v[40:43]
	v_mfma_f32_16x16x32_bf16 v[32:35], v[164:167], v[198:201], v[32:35]
	v_mfma_f32_16x16x32_bf16 v[24:27], v[156:159], v[206:209], v[24:27]
	v_mfma_f32_16x16x32_bf16 v[16:19], v[164:167], v[206:209], v[16:19]
	v_mfma_f32_16x16x32_bf16 v[8:11], v[156:159], v[214:217], v[8:11]
	v_mfma_f32_16x16x32_bf16 v[0:3], v[164:167], v[214:217], v[0:3]
	v_mfma_f32_16x16x32_bf16 v[60:63], v[168:171], v[184:187], 0
	v_mfma_f32_16x16x32_bf16 v[52:55], v[176:179], v[184:187], 0
	v_mfma_f32_16x16x32_bf16 v[44:47], v[168:171], v[194:197], 0
	v_mfma_f32_16x16x32_bf16 v[36:39], v[176:179], v[194:197], 0
	v_mfma_f32_16x16x32_bf16 v[28:31], v[168:171], v[202:205], 0
	v_mfma_f32_16x16x32_bf16 v[20:23], v[176:179], v[202:205], 0
	v_mfma_f32_16x16x32_bf16 v[12:15], v[168:171], v[210:213], 0
	v_mfma_f32_16x16x32_bf16 v[4:7], v[176:179], v[210:213], 0
	v_mfma_f32_16x16x32_bf16 v[60:63], v[172:175], v[190:193], v[60:63]
	v_mfma_f32_16x16x32_bf16 v[52:55], v[180:183], v[190:193], v[52:55]
	v_mfma_f32_16x16x32_bf16 v[44:47], v[172:175], v[198:201], v[44:47]
	v_mfma_f32_16x16x32_bf16 v[36:39], v[180:183], v[198:201], v[36:39]
	v_mfma_f32_16x16x32_bf16 v[28:31], v[172:175], v[206:209], v[28:31]
	v_mfma_f32_16x16x32_bf16 v[20:23], v[180:183], v[206:209], v[20:23]
	v_mfma_f32_16x16x32_bf16 v[12:15], v[172:175], v[214:217], v[12:15]
	v_mfma_f32_16x16x32_bf16 v[4:7], v[180:183], v[214:217], v[4:7]
	s_setprio 0
	s_barrier
	s_add_i32 s52, 0, 0x18000
	v_add_u32_e32 v155, s52, v149
	s_add_i32 s53, 0, 0x1c000
	ds_read_b128 v[144:147], v155
	ds_read_b128 v[156:159], v155 offset:1024
	ds_read_b128 v[160:163], v155 offset:2048
	ds_read_b128 v[164:167], v155 offset:3072
	v_add_u32_e32 v155, s53, v149
	ds_read_b128 v[168:171], v155
	ds_read_b128 v[172:175], v155 offset:1024
	ds_read_b128 v[176:179], v155 offset:2048
	ds_read_b128 v[180:183], v155 offset:3072
	s_add_u32 s26, s26, 0x40000
	s_addc_u32 s27, s27, 0
	s_mov_b32 m0, s36
	v_lshl_add_u64 v[226:227], s[26:27], 0, v[134:135]
	ds_read_b128 v[184:187], v153 offset:32768
	ds_read_b128 v[190:193], v153 offset:33792
	ds_read_b128 v[194:197], v153 offset:34816
	ds_read_b128 v[198:201], v153 offset:35840
	ds_read_b128 v[202:205], v153 offset:36864
	ds_read_b128 v[206:209], v153 offset:37888
	ds_read_b128 v[210:213], v153 offset:38912
	ds_read_b128 v[214:217], v153 offset:39936
	global_load_lds_dwordx4 v[226:227], off
	v_lshl_add_u64 v[226:227], s[26:27], 0, v[130:131]
	s_mov_b32 m0, s37
	s_nop 0
	global_load_lds_dwordx4 v[226:227], off
	s_waitcnt vmcnt(8)
	s_waitcnt lgkmcnt(0)
	s_barrier
	s_setprio 1
	v_mfma_f32_16x16x32_bf16 v[116:119], v[144:147], v[184:187], v[116:119]
	v_mfma_f32_16x16x32_bf16 v[112:115], v[160:163], v[184:187], v[112:115]
	v_mfma_f32_16x16x32_bf16 v[100:103], v[144:147], v[194:197], v[100:103]
	v_mfma_f32_16x16x32_bf16 v[96:99], v[160:163], v[194:197], v[96:99]
	v_mfma_f32_16x16x32_bf16 v[84:87], v[144:147], v[202:205], v[84:87]
	v_mfma_f32_16x16x32_bf16 v[80:83], v[160:163], v[202:205], v[80:83]
	v_mfma_f32_16x16x32_bf16 v[72:75], v[144:147], v[210:213], v[72:75]
	v_mfma_f32_16x16x32_bf16 v[64:67], v[160:163], v[210:213], v[64:67]
	v_mfma_f32_16x16x32_bf16 v[116:119], v[156:159], v[190:193], v[116:119]
	v_mfma_f32_16x16x32_bf16 v[112:115], v[164:167], v[190:193], v[112:115]
	v_mfma_f32_16x16x32_bf16 v[100:103], v[156:159], v[198:201], v[100:103]
	v_mfma_f32_16x16x32_bf16 v[96:99], v[164:167], v[198:201], v[96:99]
	v_mfma_f32_16x16x32_bf16 v[84:87], v[156:159], v[206:209], v[84:87]
	v_mfma_f32_16x16x32_bf16 v[80:83], v[164:167], v[206:209], v[80:83]
	v_mfma_f32_16x16x32_bf16 v[72:75], v[156:159], v[214:217], v[72:75]
	v_mfma_f32_16x16x32_bf16 v[64:67], v[164:167], v[214:217], v[64:67]
	v_mfma_f32_16x16x32_bf16 v[124:127], v[168:171], v[184:187], v[124:127]
	v_mfma_f32_16x16x32_bf16 v[120:123], v[176:179], v[184:187], v[120:123]
	v_mfma_f32_16x16x32_bf16 v[108:111], v[168:171], v[194:197], v[108:111]
	v_mfma_f32_16x16x32_bf16 v[104:107], v[176:179], v[194:197], v[104:107]
	v_mfma_f32_16x16x32_bf16 v[92:95], v[168:171], v[202:205], v[92:95]
	v_mfma_f32_16x16x32_bf16 v[88:91], v[176:179], v[202:205], v[88:91]
	v_mfma_f32_16x16x32_bf16 v[76:79], v[168:171], v[210:213], v[76:79]
	v_mfma_f32_16x16x32_bf16 v[68:71], v[176:179], v[210:213], v[68:71]
	v_mfma_f32_16x16x32_bf16 v[124:127], v[172:175], v[190:193], v[124:127]
	v_mfma_f32_16x16x32_bf16 v[120:123], v[180:183], v[190:193], v[120:123]
	v_mfma_f32_16x16x32_bf16 v[108:111], v[172:175], v[198:201], v[108:111]
	v_mfma_f32_16x16x32_bf16 v[104:107], v[180:183], v[198:201], v[104:107]
	v_mfma_f32_16x16x32_bf16 v[92:95], v[172:175], v[206:209], v[92:95]
	v_mfma_f32_16x16x32_bf16 v[88:91], v[180:183], v[206:209], v[88:91]
	v_mfma_f32_16x16x32_bf16 v[76:79], v[172:175], v[214:217], v[76:79]
	v_mfma_f32_16x16x32_bf16 v[68:71], v[180:183], v[214:217], v[68:71]
	s_setprio 0
	s_barrier
; #define PG8_STAGE(bufoff, gbase, voff) do { _Pragma("unroll") for (int _i = 0; _i < 2; ++_i) \
;         __builtin_amdgcn_global_load_lds((const unsigned*)((const char*)(gbase) + (voff)[_i]), (PG8_LAS unsigned*)(lds + (bufoff) + ldsw + _i * 8192), 16, 0, 0); } while (0)
; #define PG8_LDA(dst, b, h) do { _Pragma("unroll") for (int m = 0; m < 4; ++m) _Pragma("unroll") for (int k = 0; k < 2; ++k) dst[m][k] = *(const PG8_LAS bf16x8*)(lds + PG8_SA(b, h) + aoff + m * 2048 + k * 1024); } while (0)
; #define PG8_LDB(dst, b, h) do { _Pragma("unroll") for (int n = 0; n < 2; ++n) _Pragma("unroll") for (int k = 0; k < 2; ++k) dst[n][k] = *(const PG8_LAS bf16x8*)(lds + PG8_SB(b, h) + boff + n * 2048 + k * 1024); } while (0)
; #define PG8_MMA(ai, bj, At, Bt) do { __builtin_amdgcn_s_setprio(1); _Pragma("unroll") for (int m = 0; m < 4; ++m) _Pragma("unroll") for (int n = 0; n < 2; ++n) _Pragma("unroll") for (int k = 0; k < 2; ++k) \
;         acc[ai][bj][m][n] = __builtin_amdgcn_mfma_f32_16x16x32_bf16(Bt[n][k], At[m][k], acc[ai][bj][m][n], 0, 0, 0); __builtin_amdgcn_s_setprio(0); } while (0)
; #define PG8_WAIT_V(n) asm volatile("s_waitcnt vmcnt(" #n ")" ::: "memory")
; template <class Epi, class Sched, bool ALIGN_EPI = false, bool SP2 = false>
; __device__ __forceinline__ void gemm_phase(PG8_LAS unsigned char* lds, const Gemm g, const Sched& S, const Epi& E) {
;     ...
;             PG8_LDB(B0, 0, 0); PG8_LDB(B1, 0, 1); PG8_SCHED; PG8_LDA(At, 0, 0); PG8_STAGE(PG8_SA(1, 1), a1 + hstep, voffA);
;             PG8_WAIT_V(8); PG8_WAIT_L(0); PG8_BAR; PG8_MMA(0, 0, At, B0); PG8_MMA(0, 1, At, B1); PG8_BAR; PG8_SCHED;
;             PG8_LDA(At, 0, 1); PG8_STAGE(PG8_SB(0, 0), b2, voffB); PG8_STAGE(PG8_SB(0, 1), b2 + hstep, voffB); PG8_STAGE(PG8_SA(0, 0), a2, voffA);
;             PG8_WAIT_V(8); PG8_WAIT_L(0); PG8_BAR; PG8_MMA(1, 0, At, B0); PG8_MMA(1, 1, At, B1); PG8_BAR; PG8_SCHED;
;             PG8_LDB(B0, 1, 0); PG8_LDB(B1, 1, 1); PG8_SCHED; PG8_LDA(At, 1, 0); PG8_STAGE(PG8_SA(0, 1), a2 + hstep, voffA);
;             PG8_WAIT_V(8); PG8_WAIT_L(0); PG8_BAR; PG8_MMA(0, 0, At, B0); PG8_MMA(0, 1, At, B1); PG8_BAR; PG8_SCHED;
;             PG8_LDA(At, 1, 1); PG8_STAGE(PG8_SB(1, 0), b3, voffB); PG8_STAGE(PG8_SB(1, 1), b3 + hstep, voffB); PG8_STAGE(PG8_SA(1, 0), a3, voffA);
;             PG8_WAIT_V(8); PG8_WAIT_L(0); PG8_BAR; PG8_MMA(1, 0, At, B0); PG8_MMA(1, 1, At, B1); PG8_BAR; PG8_SCHED;
	s_add_i32 s26, s52, s30
	v_lshl_add_u64 v[218:219], v[218:219], 0, s[6:7]
	s_mov_b32 m0, s26
	ds_read_b128 v[184:187], v153 offset:49152
	ds_read_b128 v[190:193], v153 offset:50176
	ds_read_b128 v[194:197], v153 offset:51200
	ds_read_b128 v[198:201], v153 offset:52224
	ds_read_b128 v[202:205], v153 offset:53248
	ds_read_b128 v[206:209], v153 offset:54272
	ds_read_b128 v[210:213], v153 offset:55296
	ds_read_b128 v[214:217], v153 offset:56320
	global_load_lds_dwordx4 v[218:219], off
	s_add_i32 m0, s26, 0x2000
	s_add_u32 s24, s24, 0x40080
	v_lshl_add_u64 v[218:219], v[220:221], 0, s[6:7]
	s_addc_u32 s25, s25, 0
	s_add_i32 s26, s53, s30
	global_load_lds_dwordx4 v[218:219], off
	v_lshl_add_u64 v[218:219], s[24:25], 0, v[132:133]
	s_mov_b32 m0, s26
	s_nop 0
	global_load_lds_dwordx4 v[218:219], off
	v_lshl_add_u64 v[218:219], s[24:25], 0, v[128:129]
	s_add_i32 m0, s26, 0x2000
	s_nop 0
	global_load_lds_dwordx4 v[218:219], off
	v_lshl_add_u64 v[218:219], v[222:223], 0, s[6:7]
	s_mov_b32 m0, s39
	s_nop 0
	global_load_lds_dwordx4 v[218:219], off
	v_lshl_add_u64 v[218:219], v[224:225], 0, s[6:7]
	s_mov_b32 m0, s40
	s_nop 0
	global_load_lds_dwordx4 v[218:219], off
	s_waitcnt vmcnt(8)
	s_waitcnt lgkmcnt(0)
	s_barrier
	s_setprio 1
	v_mfma_f32_16x16x32_bf16 v[56:59], v[144:147], v[184:187], v[56:59]
	v_mfma_f32_16x16x32_bf16 v[48:51], v[160:163], v[184:187], v[48:51]
	v_mfma_f32_16x16x32_bf16 v[40:43], v[144:147], v[194:197], v[40:43]
	v_mfma_f32_16x16x32_bf16 v[32:35], v[160:163], v[194:197], v[32:35]
	v_mfma_f32_16x16x32_bf16 v[24:27], v[144:147], v[202:205], v[24:27]
	v_mfma_f32_16x16x32_bf16 v[16:19], v[160:163], v[202:205], v[16:19]
	v_mfma_f32_16x16x32_bf16 v[8:11], v[144:147], v[210:213], v[8:11]
	v_mfma_f32_16x16x32_bf16 v[0:3], v[160:163], v[210:213], v[0:3]
	v_mfma_f32_16x16x32_bf16 v[56:59], v[156:159], v[190:193], v[56:59]
	v_mfma_f32_16x16x32_bf16 v[48:51], v[164:167], v[190:193], v[48:51]
	v_mfma_f32_16x16x32_bf16 v[40:43], v[156:159], v[198:201], v[40:43]
	v_mfma_f32_16x16x32_bf16 v[32:35], v[164:167], v[198:201], v[32:35]
	v_mfma_f32_16x16x32_bf16 v[24:27], v[156:159], v[206:209], v[24:27]
	v_mfma_f32_16x16x32_bf16 v[16:19], v[164:167], v[206:209], v[16:19]
	v_mfma_f32_16x16x32_bf16 v[8:11], v[156:159], v[214:217], v[8:11]
	v_mfma_f32_16x16x32_bf16 v[0:3], v[164:167], v[214:217], v[0:3]
	v_mfma_f32_16x16x32_bf16 v[60:63], v[168:171], v[184:187], v[60:63]
	v_mfma_f32_16x16x32_bf16 v[52:55], v[176:179], v[184:187], v[52:55]
	v_mfma_f32_16x16x32_bf16 v[44:47], v[168:171], v[194:197], v[44:47]
	v_mfma_f32_16x16x32_bf16 v[36:39], v[176:179], v[194:197], v[36:39]
	v_mfma_f32_16x16x32_bf16 v[28:31], v[168:171], v[202:205], v[28:31]
	v_mfma_f32_16x16x32_bf16 v[20:23], v[176:179], v[202:205], v[20:23]
	v_mfma_f32_16x16x32_bf16 v[12:15], v[168:171], v[210:213], v[12:15]
	v_mfma_f32_16x16x32_bf16 v[4:7], v[176:179], v[210:213], v[4:7]
	v_mfma_f32_16x16x32_bf16 v[60:63], v[172:175], v[190:193], v[60:63]
	v_mfma_f32_16x16x32_bf16 v[52:55], v[180:183], v[190:193], v[52:55]
	v_mfma_f32_16x16x32_bf16 v[44:47], v[172:175], v[198:201], v[44:47]
	v_mfma_f32_16x16x32_bf16 v[36:39], v[180:183], v[198:201], v[36:39]
	v_mfma_f32_16x16x32_bf16 v[28:31], v[172:175], v[206:209], v[28:31]
	v_mfma_f32_16x16x32_bf16 v[20:23], v[180:183], v[206:209], v[20:23]
	v_mfma_f32_16x16x32_bf16 v[12:15], v[172:175], v[214:217], v[12:15]
	v_mfma_f32_16x16x32_bf16 v[4:7], v[180:183], v[214:217], v[4:7]
	s_setprio 0
	s_barrier
	s_add_i32 s51, s51, 2
	s_add_u32 s22, s22, 0x100
	s_addc_u32 s23, s23, 0
	s_add_u32 s49, s49, 0x100
	s_addc_u32 s50, s50, 0
	s_branch .LBB0_782
.Lp6_plain:
	ds_read_b128 v[144:147], v151
	ds_read_b128 v[156:159], v151 offset:1024
	ds_read_b128 v[160:163], v151 offset:2048
	ds_read_b128 v[164:167], v151 offset:3072
	ds_read_b128 v[168:171], v152
	ds_read_b128 v[172:175], v152 offset:1024
	ds_read_b128 v[176:179], v152 offset:2048
	ds_read_b128 v[180:183], v152 offset:3072
	s_add_u32 s24, s22, 0xfffc0080
	s_addc_u32 s25, s23, -1
	s_cmp_eq_u32 s51, 12
	s_cselect_b32 s27, s17, s25
	s_cselect_b32 s26, s47, s24
	s_cselect_b32 s25, s15, s50
	s_cselect_b32 s24, s48, s49
	v_lshl_add_u64 v[218:219], s[22:23], 0, v[136:137]
	s_add_i32 m0, s34, 0xc000
	ds_read_b128 v[184:187], v153
	ds_read_b128 v[190:193], v153 offset:1024
	ds_read_b128 v[194:197], v153 offset:2048
	ds_read_b128 v[198:201], v153 offset:3072
	ds_read_b128 v[202:205], v153 offset:4096
	ds_read_b128 v[206:209], v153 offset:5120
	ds_read_b128 v[210:213], v153 offset:6144
	ds_read_b128 v[214:217], v153 offset:7168
	global_load_lds_dwordx4 v[218:219], off
	v_lshl_add_u64 v[218:219], s[22:23], 0, v[138:139]
	s_add_i32 m0, s34, 0xe000
	s_nop 0
	global_load_lds_dwordx4 v[218:219], off
	s_waitcnt vmcnt(16)
	s_waitcnt lgkmcnt(0)
	s_barrier
; #define PG8_STAGE(bufoff, gbase, voff) do { _Pragma("unroll") for (int _i = 0; _i < 2; ++_i) \
;         __builtin_amdgcn_global_load_lds((const unsigned*)((const char*)(gbase) + (voff)[_i]), (PG8_LAS unsigned*)(lds + (bufoff) + ldsw + _i * 8192), 16, 0, 0); } while (0)
; #define PG8_LDA(dst, b, h) do { _Pragma("unroll") for (int m = 0; m < 4; ++m) _Pragma("unroll") for (int k = 0; k < 2; ++k) dst[m][k] = *(const PG8_LAS bf16x8*)(lds + PG8_SA(b, h) + aoff + m * 2048 + k * 1024); } while (0)
; #define PG8_LDB(dst, b, h) do { _Pragma("unroll") for (int n = 0; n < 2; ++n) _Pragma("unroll") for (int k = 0; k < 2; ++k) dst[n][k] = *(const PG8_LAS bf16x8*)(lds + PG8_SB(b, h) + boff + n * 2048 + k * 1024); } while (0)
; #define PG8_MMA(ai, bj, At, Bt) do { __builtin_amdgcn_s_setprio(1); _Pragma("unroll") for (int m = 0; m < 4; ++m) _Pragma("unroll") for (int n = 0; n < 2; ++n) _Pragma("unroll") for (int k = 0; k < 2; ++k) \
;         acc[ai][bj][m][n] = __builtin_amdgcn_mfma_f32_16x16x32_bf16(Bt[n][k], At[m][k], acc[ai][bj][m][n], 0, 0, 0); __builtin_amdgcn_s_setprio(0); } while (0)
; #define PG8_WAIT_V(n) asm volatile("s_waitcnt vmcnt(" #n ")" ::: "memory")
; #define PG8_WAIT_L(n) asm volatile("s_waitcnt lgkmcnt(" #n ")" ::: "memory")
; #define PG8_BAR __builtin_amdgcn_s_barrier()
; #define PG8_SCHED __builtin_amdgcn_sched_barrier(0)
; template <class Epi, class Sched, bool ALIGN_EPI = false, bool SP2 = false>
; __device__ __forceinline__ void gemm_phase(PG8_LAS unsigned char* lds, const Gemm g, const Sched& S, const Epi& E) {
;     ...
;             PG8_WAIT_V(8); PG8_WAIT_L(0); PG8_BAR; PG8_MMA(0, 0, At, B0); PG8_MMA(0, 1, At, B1); PG8_BAR; PG8_SCHED;
;             PG8_LDA(At, 0, 1); PG8_STAGE(PG8_SB(0, 0), b2, voffB); PG8_STAGE(PG8_SB(0, 1), b2 + hstep, voffB); PG8_STAGE(PG8_SA(0, 0), a2, voffA);
;             PG8_WAIT_V(8); PG8_WAIT_L(0); PG8_BAR; PG8_MMA(1, 0, At, B0); PG8_MMA(1, 1, At, B1); PG8_BAR; PG8_SCHED;
;             PG8_LDB(B0, 1, 0); PG8_LDB(B1, 1, 1); PG8_SCHED; PG8_LDA(At, 1, 0); PG8_STAGE(PG8_SA(0, 1), a2 + hstep, voffA);
;             PG8_WAIT_V(8); PG8_WAIT_L(0); PG8_BAR; PG8_MMA(0, 0, At, B0); PG8_MMA(0, 1, At, B1); PG8_BAR; PG8_SCHED;
	s_setprio 1
	v_mfma_f32_16x16x32_bf16 v[116:119], v[144:147], v[184:187], 0
	v_mfma_f32_16x16x32_bf16 v[112:115], v[160:163], v[184:187], 0
	v_mfma_f32_16x16x32_bf16 v[100:103], v[144:147], v[194:197], 0
	v_mfma_f32_16x16x32_bf16 v[96:99], v[160:163], v[194:197], 0
	v_mfma_f32_16x16x32_bf16 v[84:87], v[144:147], v[202:205], 0
	v_mfma_f32_16x16x32_bf16 v[80:83], v[160:163], v[202:205], 0
	v_mfma_f32_16x16x32_bf16 v[72:75], v[144:147], v[210:213], 0
	v_mfma_f32_16x16x32_bf16 v[64:67], v[160:163], v[210:213], 0
	v_mfma_f32_16x16x32_bf16 v[116:119], v[156:159], v[190:193], v[116:119]
	v_mfma_f32_16x16x32_bf16 v[112:115], v[164:167], v[190:193], v[112:115]
	v_mfma_f32_16x16x32_bf16 v[100:103], v[156:159], v[198:201], v[100:103]
	v_mfma_f32_16x16x32_bf16 v[96:99], v[164:167], v[198:201], v[96:99]
	v_mfma_f32_16x16x32_bf16 v[84:87], v[156:159], v[206:209], v[84:87]
	v_mfma_f32_16x16x32_bf16 v[80:83], v[164:167], v[206:209], v[80:83]
	v_mfma_f32_16x16x32_bf16 v[72:75], v[156:159], v[214:217], v[72:75]
	v_mfma_f32_16x16x32_bf16 v[64:67], v[164:167], v[214:217], v[64:67]
	v_mfma_f32_16x16x32_bf16 v[124:127], v[168:171], v[184:187], 0
	v_mfma_f32_16x16x32_bf16 v[120:123], v[176:179], v[184:187], 0
	v_mfma_f32_16x16x32_bf16 v[108:111], v[168:171], v[194:197], 0
	v_mfma_f32_16x16x32_bf16 v[104:107], v[176:179], v[194:197], 0
	v_mfma_f32_16x16x32_bf16 v[92:95], v[168:171], v[202:205], 0
	v_mfma_f32_16x16x32_bf16 v[88:91], v[176:179], v[202:205], 0
	v_mfma_f32_16x16x32_bf16 v[76:79], v[168:171], v[210:213], 0
	v_mfma_f32_16x16x32_bf16 v[68:71], v[176:179], v[210:213], 0
	v_mfma_f32_16x16x32_bf16 v[124:127], v[172:175], v[190:193], v[124:127]
	v_mfma_f32_16x16x32_bf16 v[120:123], v[180:183], v[190:193], v[120:123]
	v_mfma_f32_16x16x32_bf16 v[108:111], v[172:175], v[198:201], v[108:111]
	v_mfma_f32_16x16x32_bf16 v[104:107], v[180:183], v[198:201], v[104:107]
	v_mfma_f32_16x16x32_bf16 v[92:95], v[172:175], v[206:209], v[92:95]
	v_mfma_f32_16x16x32_bf16 v[88:91], v[180:183], v[206:209], v[88:91]
	v_mfma_f32_16x16x32_bf16 v[76:79], v[172:175], v[214:217], v[76:79]
	v_mfma_f32_16x16x32_bf16 v[68:71], v[180:183], v[214:217], v[68:71]
	s_setprio 0
	s_barrier
	s_add_i32 s52, s43, s30
	v_lshl_add_u64 v[218:219], s[24:25], 0, v[132:133]
	s_mov_b32 m0, s52
	ds_read_b128 v[184:187], v153 offset:16384
	ds_read_b128 v[190:193], v153 offset:17408
	ds_read_b128 v[194:197], v153 offset:18432
	ds_read_b128 v[198:201], v153 offset:19456
	ds_read_b128 v[202:205], v153 offset:20480
	ds_read_b128 v[206:209], v153 offset:21504
	ds_read_b128 v[210:213], v153 offset:22528
	ds_read_b128 v[214:217], v153 offset:23552
	global_load_lds_dwordx4 v[218:219], off
	s_add_i32 m0, s52, 0x2000
	s_add_u32 s52, s24, 0x40000
	v_lshl_add_u64 v[220:221], s[24:25], 0, v[128:129]
	s_addc_u32 s53, s25, 0
	s_add_i32 s54, s44, s30
	global_load_lds_dwordx4 v[220:221], off
	v_lshl_add_u64 v[222:223], s[52:53], 0, v[132:133]
	s_mov_b32 m0, s54
	v_lshl_add_u64 v[224:225], s[26:27], 0, v[130:131]
	global_load_lds_dwordx4 v[222:223], off
	v_lshl_add_u64 v[222:223], s[52:53], 0, v[128:129]
	s_add_i32 m0, s54, 0x2000
	s_nop 0
	global_load_lds_dwordx4 v[222:223], off
	v_lshl_add_u64 v[222:223], s[26:27], 0, v[134:135]
	s_mov_b32 m0, s34
	s_nop 0
	global_load_lds_dwordx4 v[222:223], off
	s_mov_b32 m0, s35
	s_nop 0
	global_load_lds_dwordx4 v[224:225], off
	s_waitcnt vmcnt(16)
	s_waitcnt lgkmcnt(0)
	s_barrier
	s_setprio 1
	v_mfma_f32_16x16x32_bf16 v[56:59], v[144:147], v[184:187], 0
	v_mfma_f32_16x16x32_bf16 v[48:51], v[160:163], v[184:187], 0
	v_mfma_f32_16x16x32_bf16 v[40:43], v[144:147], v[194:197], 0
	v_mfma_f32_16x16x32_bf16 v[32:35], v[160:163], v[194:197], 0
	v_mfma_f32_16x16x32_bf16 v[24:27], v[144:147], v[202:205], 0
	v_mfma_f32_16x16x32_bf16 v[16:19], v[160:163], v[202:205], 0
	v_mfma_f32_16x16x32_bf16 v[8:11], v[144:147], v[210:213], 0
	v_mfma_f32_16x16x32_bf16 v[0:3], v[160:163], v[210:213], 0
	v_mfma_f32_16x16x32_bf16 v[56:59], v[156:159], v[190:193], v[56:59]
	v_mfma_f32_16x16x32_bf16 v[48:51], v[164:167], v[190:193], v[48:51]
	v_mfma_f32_16x16x32_bf16 v[40:43], v[156:159], v[198:201], v[40:43]
	v_mfma_f32_16x16x32_bf16 v[32:35], v[164:167], v[198:201], v[32:35]
	v_mfma_f32_16x16x32_bf16 v[24:27], v[156:159], v[206:209], v[24:27]
	v_mfma_f32_16x16x32_bf16 v[16:19], v[164:167], v[206:209], v[16:19]
	v_mfma_f32_16x16x32_bf16 v[8:11], v[156:159], v[214:217], v[8:11]
	v_mfma_f32_16x16x32_bf16 v[0:3], v[164:167], v[214:217], v[0:3]
	v_mfma_f32_16x16x32_bf16 v[60:63], v[168:171], v[184:187], 0
	v_mfma_f32_16x16x32_bf16 v[52:55], v[176:179], v[184:187], 0
	v_mfma_f32_16x16x32_bf16 v[44:47], v[168:171], v[194:197], 0
	v_mfma_f32_16x16x32_bf16 v[36:39], v[176:179], v[194:197], 0
	v_mfma_f32_16x16x32_bf16 v[28:31], v[168:171], v[202:205], 0
	v_mfma_f32_16x16x32_bf16 v[20:23], v[176:179], v[202:205], 0
	v_mfma_f32_16x16x32_bf16 v[12:15], v[168:171], v[210:213], 0
	v_mfma_f32_16x16x32_bf16 v[4:7], v[176:179], v[210:213], 0
	v_mfma_f32_16x16x32_bf16 v[60:63], v[172:175], v[190:193], v[60:63]
	v_mfma_f32_16x16x32_bf16 v[52:55], v[180:183], v[190:193], v[52:55]
	v_mfma_f32_16x16x32_bf16 v[44:47], v[172:175], v[198:201], v[44:47]
	v_mfma_f32_16x16x32_bf16 v[36:39], v[180:183], v[198:201], v[36:39]
	v_mfma_f32_16x16x32_bf16 v[28:31], v[172:175], v[206:209], v[28:31]
	v_mfma_f32_16x16x32_bf16 v[20:23], v[180:183], v[206:209], v[20:23]
	v_mfma_f32_16x16x32_bf16 v[12:15], v[172:175], v[214:217], v[12:15]
	v_mfma_f32_16x16x32_bf16 v[4:7], v[180:183], v[214:217], v[4:7]
	s_setprio 0
	s_barrier
; #define PG8_STAGE(bufoff, gbase, voff) do { _Pragma("unroll") for (int _i = 0; _i < 2; ++_i) \
;         __builtin_amdgcn_global_load_lds((const unsigned*)((const char*)(gbase) + (voff)[_i]), (PG8_LAS unsigned*)(lds + (bufoff) + ldsw + _i * 8192), 16, 0, 0); } while (0)
; #define PG8_LDA(dst, b, h) do { _Pragma("unroll") for (int m = 0; m < 4; ++m) _Pragma("unroll") for (int k = 0; k < 2; ++k) dst[m][k] = *(const PG8_LAS bf16x8*)(lds + PG8_SA(b, h) + aoff + m * 2048 + k * 1024); } while (0)
; #define PG8_LDB(dst, b, h) do { _Pragma("unroll") for (int n = 0; n < 2; ++n) _Pragma("unroll") for (int k = 0; k < 2; ++k) dst[n][k] = *(const PG8_LAS bf16x8*)(lds + PG8_SB(b, h) + boff + n * 2048 + k * 1024); } while (0)
; #define PG8_MMA(ai, bj, At, Bt) do { __builtin_amdgcn_s_setprio(1); _Pragma("unroll") for (int m = 0; m < 4; ++m) _Pragma("unroll") for (int n = 0; n < 2; ++n) _Pragma("unroll") for (int k = 0; k < 2; ++k) \
;         acc[ai][bj][m][n] = __builtin_amdgcn_mfma_f32_16x16x32_bf16(Bt[n][k], At[m][k], acc[ai][bj][m][n], 0, 0, 0); __builtin_amdgcn_s_setprio(0); } while (0)
; #define PG8_WAIT_V(n) asm volatile("s_waitcnt vmcnt(" #n ")" ::: "memory")
; #define PG8_WAIT_L(n) asm volatile("s_waitcnt lgkmcnt(" #n ")" ::: "memory")
; #define PG8_BAR __builtin_amdgcn_s_barrier()
; #define PG8_SCHED __builtin_amdgcn_sched_barrier(0)
; template <class Epi, class Sched, bool ALIGN_EPI = false, bool SP2 = false>
; __device__ __forceinline__ void gemm_phase(PG8_LAS unsigned char* lds, const Gemm g, const Sched& S, const Epi& E) {
;     ...
;             PG8_LDB(B0, 1, 0); PG8_LDB(B1, 1, 1); PG8_SCHED; PG8_LDA(At, 1, 0); PG8_STAGE(PG8_SA(0, 1), a2 + hstep, voffA);
;             PG8_WAIT_V(8); PG8_WAIT_L(0); PG8_BAR; PG8_MMA(0, 0, At, B0); PG8_MMA(0, 1, At, B1); PG8_BAR; PG8_SCHED;
;             PG8_LDA(At, 1, 1); PG8_STAGE(PG8_SB(1, 0), b3, voffB); PG8_STAGE(PG8_SB(1, 1), b3 + hstep, voffB); PG8_STAGE(PG8_SA(1, 0), a3, voffA);
;             PG8_WAIT_V(8); PG8_WAIT_L(0); PG8_BAR; PG8_MMA(1, 0, At, B0); PG8_MMA(1, 1, At, B1); PG8_BAR; PG8_SCHED;
	s_add_i32 s52, 0, 0x18000
	v_add_u32_e32 v155, s52, v149
	s_add_i32 s53, 0, 0x1c000
	ds_read_b128 v[144:147], v155
	ds_read_b128 v[156:159], v155 offset:1024
	ds_read_b128 v[160:163], v155 offset:2048
	ds_read_b128 v[164:167], v155 offset:3072
	v_add_u32_e32 v155, s53, v149
	ds_read_b128 v[168:171], v155
	ds_read_b128 v[172:175], v155 offset:1024
	ds_read_b128 v[176:179], v155 offset:2048
	ds_read_b128 v[180:183], v155 offset:3072
	s_add_u32 s26, s26, 0x40000
	s_addc_u32 s27, s27, 0
	s_mov_b32 m0, s36
	v_lshl_add_u64 v[226:227], s[26:27], 0, v[134:135]
	ds_read_b128 v[184:187], v153 offset:32768
	ds_read_b128 v[190:193], v153 offset:33792
	ds_read_b128 v[194:197], v153 offset:34816
	ds_read_b128 v[198:201], v153 offset:35840
	ds_read_b128 v[202:205], v153 offset:36864
	ds_read_b128 v[206:209], v153 offset:37888
	ds_read_b128 v[210:213], v153 offset:38912
	ds_read_b128 v[214:217], v153 offset:39936
	global_load_lds_dwordx4 v[226:227], off
	v_lshl_add_u64 v[226:227], s[26:27], 0, v[130:131]
	s_mov_b32 m0, s37
	s_nop 0
	global_load_lds_dwordx4 v[226:227], off
	s_waitcnt vmcnt(8)
	s_waitcnt lgkmcnt(0)
	s_barrier
	s_setprio 1
	v_mfma_f32_16x16x32_bf16 v[116:119], v[144:147], v[184:187], v[116:119]
	v_mfma_f32_16x16x32_bf16 v[112:115], v[160:163], v[184:187], v[112:115]
	v_mfma_f32_16x16x32_bf16 v[100:103], v[144:147], v[194:197], v[100:103]
	v_mfma_f32_16x16x32_bf16 v[96:99], v[160:163], v[194:197], v[96:99]
	v_mfma_f32_16x16x32_bf16 v[84:87], v[144:147], v[202:205], v[84:87]
	v_mfma_f32_16x16x32_bf16 v[80:83], v[160:163], v[202:205], v[80:83]
	v_mfma_f32_16x16x32_bf16 v[72:75], v[144:147], v[210:213], v[72:75]
	v_mfma_f32_16x16x32_bf16 v[64:67], v[160:163], v[210:213], v[64:67]
	v_mfma_f32_16x16x32_bf16 v[116:119], v[156:159], v[190:193], v[116:119]
	v_mfma_f32_16x16x32_bf16 v[112:115], v[164:167], v[190:193], v[112:115]
	v_mfma_f32_16x16x32_bf16 v[100:103], v[156:159], v[198:201], v[100:103]
	v_mfma_f32_16x16x32_bf16 v[96:99], v[164:167], v[198:201], v[96:99]
	v_mfma_f32_16x16x32_bf16 v[84:87], v[156:159], v[206:209], v[84:87]
	v_mfma_f32_16x16x32_bf16 v[80:83], v[164:167], v[206:209], v[80:83]
	v_mfma_f32_16x16x32_bf16 v[72:75], v[156:159], v[214:217], v[72:75]
	v_mfma_f32_16x16x32_bf16 v[64:67], v[164:167], v[214:217], v[64:67]
	v_mfma_f32_16x16x32_bf16 v[124:127], v[168:171], v[184:187], v[124:127]
	v_mfma_f32_16x16x32_bf16 v[120:123], v[176:179], v[184:187], v[120:123]
	v_mfma_f32_16x16x32_bf16 v[108:111], v[168:171], v[194:197], v[108:111]
	v_mfma_f32_16x16x32_bf16 v[104:107], v[176:179], v[194:197], v[104:107]
	v_mfma_f32_16x16x32_bf16 v[92:95], v[168:171], v[202:205], v[92:95]
	v_mfma_f32_16x16x32_bf16 v[88:91], v[176:179], v[202:205], v[88:91]
	v_mfma_f32_16x16x32_bf16 v[76:79], v[168:171], v[210:213], v[76:79]
	v_mfma_f32_16x16x32_bf16 v[68:71], v[176:179], v[210:213], v[68:71]
	v_mfma_f32_16x16x32_bf16 v[124:127], v[172:175], v[190:193], v[124:127]
	v_mfma_f32_16x16x32_bf16 v[120:123], v[180:183], v[190:193], v[120:123]
	v_mfma_f32_16x16x32_bf16 v[108:111], v[172:175], v[198:201], v[108:111]
	v_mfma_f32_16x16x32_bf16 v[104:107], v[180:183], v[198:201], v[104:107]
	v_mfma_f32_16x16x32_bf16 v[92:95], v[172:175], v[206:209], v[92:95]
	v_mfma_f32_16x16x32_bf16 v[88:91], v[180:183], v[206:209], v[88:91]
	v_mfma_f32_16x16x32_bf16 v[76:79], v[172:175], v[214:217], v[76:79]
	v_mfma_f32_16x16x32_bf16 v[68:71], v[180:183], v[214:217], v[68:71]
	s_setprio 0
	s_barrier
	s_add_i32 s26, s52, s30
	v_lshl_add_u64 v[218:219], v[218:219], 0, s[6:7]
	s_mov_b32 m0, s26
	ds_read_b128 v[184:187], v153 offset:49152
	ds_read_b128 v[190:193], v153 offset:50176
	ds_read_b128 v[194:197], v153 offset:51200
	ds_read_b128 v[198:201], v153 offset:52224
	ds_read_b128 v[202:205], v153 offset:53248
	ds_read_b128 v[206:209], v153 offset:54272
	ds_read_b128 v[210:213], v153 offset:55296
	ds_read_b128 v[214:217], v153 offset:56320
	global_load_lds_dwordx4 v[218:219], off
	s_add_i32 m0, s26, 0x2000
	s_add_u32 s24, s24, 0x40080
	v_lshl_add_u64 v[218:219], v[220:221], 0, s[6:7]
	s_addc_u32 s25, s25, 0
	s_add_i32 s26, s53, s30
	global_load_lds_dwordx4 v[218:219], off
	v_lshl_add_u64 v[218:219], s[24:25], 0, v[132:133]
	s_mov_b32 m0, s26
	s_nop 0
	global_load_lds_dwordx4 v[218:219], off
	v_lshl_add_u64 v[218:219], s[24:25], 0, v[128:129]
	s_add_i32 m0, s26, 0x2000
	s_nop 0
	global_load_lds_dwordx4 v[218:219], off
	v_lshl_add_u64 v[218:219], v[222:223], 0, s[6:7]
	s_mov_b32 m0, s39
	s_nop 0
	global_load_lds_dwordx4 v[218:219], off
	v_lshl_add_u64 v[218:219], v[224:225], 0, s[6:7]
	s_mov_b32 m0, s40
	s_nop 0
	global_load_lds_dwordx4 v[218:219], off
	s_waitcnt vmcnt(8)
	s_waitcnt lgkmcnt(0)
	s_barrier
	s_setprio 1
	v_mfma_f32_16x16x32_bf16 v[56:59], v[144:147], v[184:187], v[56:59]
	v_mfma_f32_16x16x32_bf16 v[48:51], v[160:163], v[184:187], v[48:51]
	v_mfma_f32_16x16x32_bf16 v[40:43], v[144:147], v[194:197], v[40:43]
	v_mfma_f32_16x16x32_bf16 v[32:35], v[160:163], v[194:197], v[32:35]
	v_mfma_f32_16x16x32_bf16 v[24:27], v[144:147], v[202:205], v[24:27]
	v_mfma_f32_16x16x32_bf16 v[16:19], v[160:163], v[202:205], v[16:19]
	v_mfma_f32_16x16x32_bf16 v[8:11], v[144:147], v[210:213], v[8:11]
	v_mfma_f32_16x16x32_bf16 v[0:3], v[160:163], v[210:213], v[0:3]
	v_mfma_f32_16x16x32_bf16 v[56:59], v[156:159], v[190:193], v[56:59]
	v_mfma_f32_16x16x32_bf16 v[48:51], v[164:167], v[190:193], v[48:51]
	v_mfma_f32_16x16x32_bf16 v[40:43], v[156:159], v[198:201], v[40:43]
	v_mfma_f32_16x16x32_bf16 v[32:35], v[164:167], v[198:201], v[32:35]
	v_mfma_f32_16x16x32_bf16 v[24:27], v[156:159], v[206:209], v[24:27]
	v_mfma_f32_16x16x32_bf16 v[16:19], v[164:167], v[206:209], v[16:19]
	v_mfma_f32_16x16x32_bf16 v[8:11], v[156:159], v[214:217], v[8:11]
	v_mfma_f32_16x16x32_bf16 v[0:3], v[164:167], v[214:217], v[0:3]
	v_mfma_f32_16x16x32_bf16 v[60:63], v[168:171], v[184:187], v[60:63]
	v_mfma_f32_16x16x32_bf16 v[52:55], v[176:179], v[184:187], v[52:55]
	v_mfma_f32_16x16x32_bf16 v[44:47], v[168:171], v[194:197], v[44:47]
	v_mfma_f32_16x16x32_bf16 v[36:39], v[176:179], v[194:197], v[36:39]
	v_mfma_f32_16x16x32_bf16 v[28:31], v[168:171], v[202:205], v[28:31]
	v_mfma_f32_16x16x32_bf16 v[20:23], v[176:179], v[202:205], v[20:23]
	v_mfma_f32_16x16x32_bf16 v[12:15], v[168:171], v[210:213], v[12:15]
	v_mfma_f32_16x16x32_bf16 v[4:7], v[176:179], v[210:213], v[4:7]
	v_mfma_f32_16x16x32_bf16 v[60:63], v[172:175], v[190:193], v[60:63]
	v_mfma_f32_16x16x32_bf16 v[52:55], v[180:183], v[190:193], v[52:55]
	v_mfma_f32_16x16x32_bf16 v[44:47], v[172:175], v[198:201], v[44:47]
	v_mfma_f32_16x16x32_bf16 v[36:39], v[180:183], v[198:201], v[36:39]
	v_mfma_f32_16x16x32_bf16 v[28:31], v[172:175], v[206:209], v[28:31]
	v_mfma_f32_16x16x32_bf16 v[20:23], v[180:183], v[206:209], v[20:23]
	v_mfma_f32_16x16x32_bf16 v[12:15], v[172:175], v[214:217], v[12:15]
	v_mfma_f32_16x16x32_bf16 v[4:7], v[180:183], v[214:217], v[4:7]
	s_setprio 0
	s_barrier
	s_add_i32 s51, s51, 2
	s_add_u32 s22, s22, 0x100
	s_addc_u32 s23, s23, 0
	s_add_u32 s49, s49, 0x100
	s_addc_u32 s50, s50, 0

; __device__ __forceinline__ unsigned pk2(float lo, float hi) { return pg8::cvt_pk_bf16(lo, hi); }
; __device__ __forceinline__ float silu_f(float x) { return x * sigmoid_f(x); }
;     __device__ __forceinline__ void operator()(const f32x4 (&acc)[2][2][4][2], const pg8::Unit& u, int wr, int wc, int fr, int fq) const {
;         const int row0 = u.pm * 256 + wr * 64 + fr, col = u.pn * 128 + wc * 32 + 8 * fq;
; #pragma unroll
;         for (int ai = 0; ai < 2; ++ai)
; #pragma unroll
;             for (int m = 0; m < 4; ++m) {
;                 const int row = row0 + ai * 128 + m * 16;
;                 const float rs = sumsq ? rsqrtf(sumsq[row] * (1.f / 1024.f) + EPS) : 1.f;
;                 float o[8];
; #pragma unroll
;                 for (int n = 0; n < 2; ++n)
; #pragma unroll
;                     for (int e = 0; e < 4; ++e) { const float g = acc[ai][0][m][n][e] * rs, up = acc[ai][1][m][n][e] * rs; o[4 * n + e] = silu_f(g) * up; }
;                 u32x4 w; w.x = pk2(o[0], o[1]); w.y = pk2(o[2], o[3]); w.z = pk2(o[4], o[5]); w.w = pk2(o[6], o[7]);
;                 *(u32x4*)(H + (size_t)row * DFF + col) = w;
.LBB0_785:
	v_lshl_add_u32 v144, s0, 8, v148
	v_mov_b32_e32 v228, v144
	v_ashrrev_i32_e32 v145, 31, v144
	v_lshl_add_u64 v[146:147], v[144:145], 2, s[10:11]
	global_load_dword v145, v[146:147], off
	global_load_dword v236, v[146:147], off offset:64
	global_load_dword v237, v[146:147], off offset:128
	global_load_dword v238, v[146:147], off offset:192
	global_load_dword v239, v[146:147], off offset:512
	global_load_dword v240, v[146:147], off offset:576
	global_load_dword v241, v[146:147], off offset:640
	global_load_dword v242, v[146:147], off offset:704
	v_lshl_or_b32 v156, s1, 7, v150
	v_readlane_b32 s0, v235, 33
	v_mov_b32_e32 v161, v114
	v_mov_b32_e32 v114, v123
	v_readlane_b32 s1, v235, 34
	v_mov_b32_e32 v158, v124
	v_mov_b32_e32 v159, v116
	v_mov_b32_e32 v116, v125
	v_mov_b32_e32 v124, v126
	v_mov_b32_e32 v125, v118
	v_mov_b32_e32 v118, v127
	v_mov_b32_e32 v126, v120
	v_mov_b32_e32 v127, v112
	v_mov_b32_e32 v112, v121
	v_mov_b32_e32 v160, v122
	v_mov_b64_e32 v[120:121], s[0:1]
	v_ashrrev_i32_e32 v157, 31, v156
	v_or_b32_e32 v164, 16, v144
	v_mad_i64_i32 v[162:163], s[0:1], v144, s46, v[120:121]
	v_lshlrev_b64 v[122:123], 1, v[156:157]
	v_ashrrev_i32_e32 v165, 31, v164
	v_lshl_add_u64 v[156:157], v[162:163], 0, v[122:123]
	v_lshl_add_u64 v[162:163], v[164:165], 2, s[10:11]
	s_waitcnt vmcnt(0)
	v_fmamk_f32 v145, v145, 0x3a800000, v154
	v_mul_f32_e32 v155, 0x4b800000, v145
	v_cmp_gt_f32_e32 vcc, s45, v145
	s_nop 1
	v_cndmask_b32_e32 v145, v145, v155, vcc
	v_rsq_f32_e32 v145, v145
	s_nop 0
	v_mul_f32_e32 v155, 0x45800000, v145
	v_cndmask_b32_e32 v166, v145, v155, vcc
	v_pk_mul_f32 v[114:115], v[114:115], v[166:167] op_sel_hi:[1,0]
	v_pk_mul_f32 v[158:159], v[158:159], v[166:167] op_sel_hi:[1,0]
	v_pk_mul_f32 v[116:117], v[116:117], v[166:167] op_sel_hi:[1,0]
	v_pk_mul_f32 v[124:125], v[124:125], v[166:167] op_sel_hi:[1,0]
	v_pk_mul_f32 v[118:119], v[118:119], v[166:167] op_sel_hi:[1,0]
	v_pk_mul_f32 v[126:127], v[126:127], v[166:167] op_sel_hi:[1,0]
	v_pk_mul_f32 v[112:113], v[112:113], v[166:167] op_sel_hi:[1,0]
	v_pk_mul_f32 v[160:161], v[160:161], v[166:167] op_sel_hi:[1,0]
	v_mul_f32_e32 v170, 0xbfb8aa3b, v115
	v_mul_f32_e32 v145, 0xbfb8aa3b, v159
	v_mul_f32_e32 v155, 0xbfb8aa3b, v117
	v_mul_f32_e32 v165, 0xbfb8aa3b, v125
	v_mul_f32_e32 v166, 0xbfb8aa3b, v119
	v_mul_f32_e32 v167, 0xbfb8aa3b, v127
	v_mul_f32_e32 v168, 0xbfb8aa3b, v113
	v_mul_f32_e32 v169, 0xbfb8aa3b, v161
	v_exp_f32_e32 v170, v170
	v_exp_f32_e32 v145, v145
	v_exp_f32_e32 v155, v155
	v_exp_f32_e32 v165, v165
	v_exp_f32_e32 v166, v166
	v_exp_f32_e32 v167, v167
	v_exp_f32_e32 v168, v168
	v_exp_f32_e32 v169, v169
	v_add_f32_e32 v170, 1.0, v170
	v_add_f32_e32 v145, 1.0, v145
	v_add_f32_e32 v155, 1.0, v155
	v_add_f32_e32 v165, 1.0, v165
	v_add_f32_e32 v166, 1.0, v166
	v_add_f32_e32 v167, 1.0, v167
	v_add_f32_e32 v168, 1.0, v168
	v_add_f32_e32 v169, 1.0, v169
	v_rcp_f32_e32 v170, v170
	v_rcp_f32_e32 v145, v145
	v_rcp_f32_e32 v155, v155
	v_rcp_f32_e32 v165, v165
	v_rcp_f32_e32 v166, v166
	v_rcp_f32_e32 v167, v167
	v_rcp_f32_e32 v168, v168
	v_rcp_f32_e32 v169, v169
	v_mul_f32_e32 v115, v115, v170
	v_mul_f32_e32 v145, v159, v145
	v_mul_f32_e32 v117, v117, v155
	v_mul_f32_e32 v125, v125, v165
	v_mul_f32_e32 v119, v119, v166
	v_mul_f32_e32 v127, v127, v167
	v_mul_f32_e32 v113, v113, v168
	v_mul_f32_e32 v155, v161, v169
	v_mul_f32_e32 v115, v114, v115
	v_mul_f32_e32 v145, v158, v145
	v_mul_f32_e32 v116, v116, v117
	v_mul_f32_e32 v117, v124, v125
	v_mul_f32_e32 v118, v118, v119
	v_mul_f32_e32 v119, v126, v127
	v_mul_f32_e32 v124, v112, v113
	v_mul_f32_e32 v125, v160, v155
	v_cvt_pk_bf16_f32 v112, v145, v116
	v_cvt_pk_bf16_f32 v113, v117, v118
	v_cvt_pk_bf16_f32 v114, v119, v124
	v_cvt_pk_bf16_f32 v115, v125, v115
	global_store_dwordx4 v[156:157], v[112:115], off
	s_nop 0
	s_nop 0
	v_mov_b32_e32 v113, v100
	v_mov_b32_e32 v100, v109
	v_mov_b32_e32 v109, v102
	v_mov_b32_e32 v102, v111
	v_mov_b32_e32 v111, v96
	v_mov_b32_e32 v96, v105
	v_mov_b32_e32 v105, v98
	v_mov_b32_e32 v98, v107
	v_mov_b32_e32 v112, v108
	v_mov_b32_e32 v108, v110
	v_mov_b32_e32 v110, v104
	v_mov_b32_e32 v104, v106
	v_or_b32_e32 v106, 32, v144
	v_mad_i64_i32 v[114:115], s[0:1], v164, s46, v[120:121]
	v_lshl_add_u64 v[114:115], v[114:115], 0, v[122:123]
	s_nop 0
	v_fmamk_f32 v107, v236, 0x3a800000, v154
	v_mul_f32_e32 v116, 0x4b800000, v107
	v_cmp_gt_f32_e32 vcc, s45, v107
	s_nop 1
	v_cndmask_b32_e32 v107, v107, v116, vcc
	v_rsq_f32_e32 v118, v107
	v_ashrrev_i32_e32 v107, 31, v106
	v_lshl_add_u64 v[116:117], v[106:107], 2, s[10:11]
	v_mul_f32_e32 v107, 0x45800000, v118
	v_cndmask_b32_e32 v118, v118, v107, vcc
	v_pk_mul_f32 v[98:99], v[98:99], v[118:119] op_sel_hi:[1,0]
	v_pk_mul_f32 v[112:113], v[112:113], v[118:119] op_sel_hi:[1,0]
	v_pk_mul_f32 v[100:101], v[100:101], v[118:119] op_sel_hi:[1,0]
	v_pk_mul_f32 v[108:109], v[108:109], v[118:119] op_sel_hi:[1,0]
	v_pk_mul_f32 v[102:103], v[102:103], v[118:119] op_sel_hi:[1,0]
	v_pk_mul_f32 v[110:111], v[110:111], v[118:119] op_sel_hi:[1,0]
	v_pk_mul_f32 v[96:97], v[96:97], v[118:119] op_sel_hi:[1,0]
	v_pk_mul_f32 v[104:105], v[104:105], v[118:119] op_sel_hi:[1,0]
	v_mul_f32_e32 v145, 0xbfb8aa3b, v99
	v_mul_f32_e32 v107, 0xbfb8aa3b, v113
	v_mul_f32_e32 v118, 0xbfb8aa3b, v101
	v_mul_f32_e32 v119, 0xbfb8aa3b, v109
	v_mul_f32_e32 v124, 0xbfb8aa3b, v103
	v_mul_f32_e32 v125, 0xbfb8aa3b, v111
	v_mul_f32_e32 v126, 0xbfb8aa3b, v97
	v_mul_f32_e32 v127, 0xbfb8aa3b, v105
	v_exp_f32_e32 v145, v145
	v_exp_f32_e32 v107, v107
	v_exp_f32_e32 v118, v118
	v_exp_f32_e32 v119, v119
	v_exp_f32_e32 v124, v124
	v_exp_f32_e32 v125, v125
	v_exp_f32_e32 v126, v126
	v_exp_f32_e32 v127, v127
; #define PG8_BAR __builtin_amdgcn_s_barrier()
; __device__ __forceinline__ unsigned pk2(float lo, float hi) { return pg8::cvt_pk_bf16(lo, hi); }
; __device__ __forceinline__ float silu_f(float x) { return x * sigmoid_f(x); }
; template <class Epi, class Sched, bool ALIGN_EPI = false, bool SP2 = false>
; __device__ __forceinline__ void gemm_phase(PG8_LAS unsigned char* lds, const Gemm g, const Sched& S, const Epi& E) {
;     ...
;         if (!has_next) break;
; #pragma unroll
;         for (int a = 0; a < 2; ++a)
; #pragma unroll
;             for (int b = 0; b < 2; ++b)
; #pragma unroll
;                 for (int m = 0; m < 4; ++m)
; #pragma unroll
;                     for (int n = 0; n < 2; ++n) acc[a][b][m][n] = (f32x4){0.f, 0.f, 0.f, 0.f};
;         cur = nxt; cA = nA; cB = nB; ++ui;
;         if constexpr (ALIGN_EPI) { if (wr == 1) PG8_BAR; }
;     __device__ __forceinline__ void operator()(const f32x4 (&acc)[2][2][4][2], const pg8::Unit& u, int wr, int wc, int fr, int fq) const {
;     ...
;                 const int row = row0 + ai * 128 + m * 16;
;                 const float rs = sumsq ? rsqrtf(sumsq[row] * (1.f / 1024.f) + EPS) : 1.f;
;                 float o[8];
; #pragma unroll
;                 for (int n = 0; n < 2; ++n)
; #pragma unroll
;                     for (int e = 0; e < 4; ++e) { const float g = acc[ai][0][m][n][e] * rs, up = acc[ai][1][m][n][e] * rs; o[4 * n + e] = silu_f(g) * up; }
;                 u32x4 w; w.x = pk2(o[0], o[1]); w.y = pk2(o[2], o[3]); w.z = pk2(o[4], o[5]); w.w = pk2(o[6], o[7]);
;                 *(u32x4*)(H + (size_t)row * DFF + col) = w;
	v_add_f32_e32 v145, 1.0, v145
	v_add_f32_e32 v107, 1.0, v107
	v_add_f32_e32 v118, 1.0, v118
	v_add_f32_e32 v119, 1.0, v119
	v_add_f32_e32 v124, 1.0, v124
	v_add_f32_e32 v125, 1.0, v125
	v_add_f32_e32 v126, 1.0, v126
	v_add_f32_e32 v127, 1.0, v127
	v_rcp_f32_e32 v145, v145
	v_rcp_f32_e32 v107, v107
	v_rcp_f32_e32 v118, v118
	v_rcp_f32_e32 v119, v119
	v_rcp_f32_e32 v124, v124
	v_rcp_f32_e32 v125, v125
	v_rcp_f32_e32 v126, v126
	v_rcp_f32_e32 v127, v127
	v_mul_f32_e32 v99, v99, v145
	v_mul_f32_e32 v107, v113, v107
	v_mul_f32_e32 v101, v101, v118
	v_mul_f32_e32 v109, v109, v119
	v_mul_f32_e32 v103, v103, v124
	v_mul_f32_e32 v111, v111, v125
	v_mul_f32_e32 v97, v97, v126
	v_mul_f32_e32 v105, v105, v127
	v_mul_f32_e32 v99, v98, v99
	v_mul_f32_e32 v107, v112, v107
	v_mul_f32_e32 v100, v100, v101
	v_mul_f32_e32 v101, v108, v109
	v_mul_f32_e32 v102, v102, v103
	v_mul_f32_e32 v103, v110, v111
	v_mul_f32_e32 v108, v96, v97
	v_mul_f32_e32 v104, v104, v105
	v_cvt_pk_bf16_f32 v96, v107, v100
	v_cvt_pk_bf16_f32 v97, v101, v102
	v_cvt_pk_bf16_f32 v98, v103, v108
	v_cvt_pk_bf16_f32 v99, v104, v99
	global_store_dwordx4 v[114:115], v[96:99], off
	s_nop 0
	s_nop 0
	v_mov_b32_e32 v97, v84
	v_mov_b32_e32 v84, v93
	v_mov_b32_e32 v93, v86
	v_mov_b32_e32 v86, v95
	v_mov_b32_e32 v95, v80
	v_mov_b32_e32 v80, v89
	v_mov_b32_e32 v89, v82
	v_mov_b32_e32 v82, v91
	v_mov_b32_e32 v96, v92
	v_mov_b32_e32 v92, v94
	v_mov_b32_e32 v94, v88
	v_mov_b32_e32 v88, v90
	v_or_b32_e32 v90, 48, v144
	v_mad_i64_i32 v[98:99], s[0:1], v106, s46, v[120:121]
	v_lshl_add_u64 v[98:99], v[98:99], 0, v[122:123]
	s_nop 0
	v_fmamk_f32 v91, v237, 0x3a800000, v154
	v_mul_f32_e32 v100, 0x4b800000, v91
	v_cmp_gt_f32_e32 vcc, s45, v91
	s_nop 1
	v_cndmask_b32_e32 v91, v91, v100, vcc
	v_rsq_f32_e32 v102, v91
	v_ashrrev_i32_e32 v91, 31, v90
	v_lshl_add_u64 v[100:101], v[90:91], 2, s[10:11]
	v_mul_f32_e32 v91, 0x45800000, v102
	v_cndmask_b32_e32 v102, v102, v91, vcc
	v_pk_mul_f32 v[82:83], v[82:83], v[102:103] op_sel_hi:[1,0]
	v_pk_mul_f32 v[96:97], v[96:97], v[102:103] op_sel_hi:[1,0]
	v_pk_mul_f32 v[84:85], v[84:85], v[102:103] op_sel_hi:[1,0]
	v_pk_mul_f32 v[92:93], v[92:93], v[102:103] op_sel_hi:[1,0]
	v_pk_mul_f32 v[86:87], v[86:87], v[102:103] op_sel_hi:[1,0]
	v_pk_mul_f32 v[94:95], v[94:95], v[102:103] op_sel_hi:[1,0]
	v_pk_mul_f32 v[80:81], v[80:81], v[102:103] op_sel_hi:[1,0]
	v_pk_mul_f32 v[88:89], v[88:89], v[102:103] op_sel_hi:[1,0]
	v_mul_f32_e32 v108, 0xbfb8aa3b, v83
	v_mul_f32_e32 v91, 0xbfb8aa3b, v97
	v_mul_f32_e32 v102, 0xbfb8aa3b, v85
	v_mul_f32_e32 v103, 0xbfb8aa3b, v93
	v_mul_f32_e32 v104, 0xbfb8aa3b, v87
	v_mul_f32_e32 v105, 0xbfb8aa3b, v95
	v_mul_f32_e32 v106, 0xbfb8aa3b, v81
	v_mul_f32_e32 v107, 0xbfb8aa3b, v89
	v_exp_f32_e32 v108, v108
	v_exp_f32_e32 v91, v91
	v_exp_f32_e32 v102, v102
	v_exp_f32_e32 v103, v103
	v_exp_f32_e32 v104, v104
	v_exp_f32_e32 v105, v105
	v_exp_f32_e32 v106, v106
	v_exp_f32_e32 v107, v107
	v_add_f32_e32 v108, 1.0, v108
	v_add_f32_e32 v91, 1.0, v91
	v_add_f32_e32 v102, 1.0, v102
	v_add_f32_e32 v103, 1.0, v103
	v_add_f32_e32 v104, 1.0, v104
	v_add_f32_e32 v105, 1.0, v105
	v_add_f32_e32 v106, 1.0, v106
	v_add_f32_e32 v107, 1.0, v107
	v_rcp_f32_e32 v108, v108
	v_rcp_f32_e32 v91, v91
	v_rcp_f32_e32 v102, v102
	v_rcp_f32_e32 v103, v103
	v_rcp_f32_e32 v104, v104
	v_rcp_f32_e32 v105, v105
	v_rcp_f32_e32 v106, v106
	v_rcp_f32_e32 v107, v107
	v_mul_f32_e32 v83, v83, v108
	v_mul_f32_e32 v91, v97, v91
	v_mul_f32_e32 v85, v85, v102
	v_mul_f32_e32 v93, v93, v103
	v_mul_f32_e32 v87, v87, v104
	v_mul_f32_e32 v95, v95, v105
	v_mul_f32_e32 v81, v81, v106
	v_mul_f32_e32 v89, v89, v107
	v_mul_f32_e32 v83, v82, v83
	v_mul_f32_e32 v91, v96, v91
	v_mul_f32_e32 v84, v84, v85
	v_mul_f32_e32 v85, v92, v93
	v_mul_f32_e32 v86, v86, v87
	v_mul_f32_e32 v87, v94, v95
	v_mul_f32_e32 v92, v80, v81
	v_mul_f32_e32 v88, v88, v89
	v_cvt_pk_bf16_f32 v80, v91, v84
	v_cvt_pk_bf16_f32 v81, v85, v86
	v_cvt_pk_bf16_f32 v82, v87, v92
	v_cvt_pk_bf16_f32 v83, v88, v83
	global_store_dwordx4 v[98:99], v[80:83], off
	s_nop 0
	s_nop 0
	v_mov_b32_e32 v80, v76
	v_mov_b32_e32 v76, v78
	v_mov_b32_e32 v78, v68
	v_mov_b32_e32 v68, v70
	v_mov_b32_e32 v81, v72
	v_mov_b32_e32 v72, v77
	v_mov_b32_e32 v77, v74
	v_mov_b32_e32 v74, v79
	v_mov_b32_e32 v79, v64
	v_mov_b32_e32 v64, v69
	v_mov_b32_e32 v69, v66
	v_mov_b32_e32 v66, v71
	s_nop 0
	v_fmamk_f32 v70, v238, 0x3a800000, v154
	v_mul_f32_e32 v71, 0x4b800000, v70
	v_cmp_gt_f32_e32 vcc, s45, v70
	s_nop 1
	v_cndmask_b32_e32 v70, v70, v71, vcc
	v_rsq_f32_e32 v82, v70
	v_mad_i64_i32 v[70:71], s[0:1], v90, s46, v[120:121]
	v_lshl_add_u64 v[70:71], v[70:71], 0, v[122:123]
	v_mul_f32_e32 v83, 0x45800000, v82
	v_cndmask_b32_e32 v82, v82, v83, vcc
	v_pk_mul_f32 v[66:67], v[66:67], v[82:83] op_sel_hi:[1,0]
	v_pk_mul_f32 v[80:81], v[80:81], v[82:83] op_sel_hi:[1,0]
	v_pk_mul_f32 v[72:73], v[72:73], v[82:83] op_sel_hi:[1,0]
	v_pk_mul_f32 v[76:77], v[76:77], v[82:83] op_sel_hi:[1,0]
	v_pk_mul_f32 v[74:75], v[74:75], v[82:83] op_sel_hi:[1,0]
	v_pk_mul_f32 v[78:79], v[78:79], v[82:83] op_sel_hi:[1,0]
	v_pk_mul_f32 v[64:65], v[64:65], v[82:83] op_sel_hi:[1,0]
	v_pk_mul_f32 v[68:69], v[68:69], v[82:83] op_sel_hi:[1,0]
	v_mul_f32_e32 v89, 0xbfb8aa3b, v67
	v_mul_f32_e32 v82, 0xbfb8aa3b, v81
	v_mul_f32_e32 v83, 0xbfb8aa3b, v73
	v_mul_f32_e32 v84, 0xbfb8aa3b, v77
	v_mul_f32_e32 v85, 0xbfb8aa3b, v75
	v_mul_f32_e32 v86, 0xbfb8aa3b, v79
	v_mul_f32_e32 v87, 0xbfb8aa3b, v65
	v_mul_f32_e32 v88, 0xbfb8aa3b, v69
	v_exp_f32_e32 v89, v89
	v_exp_f32_e32 v82, v82
	v_exp_f32_e32 v83, v83
	v_exp_f32_e32 v84, v84
	v_exp_f32_e32 v85, v85
	v_exp_f32_e32 v86, v86
	v_exp_f32_e32 v87, v87
	v_exp_f32_e32 v88, v88
	v_add_f32_e32 v89, 1.0, v89
	v_add_f32_e32 v82, 1.0, v82
	v_add_f32_e32 v83, 1.0, v83
	v_add_f32_e32 v84, 1.0, v84
	v_add_f32_e32 v85, 1.0, v85
	v_add_f32_e32 v86, 1.0, v86
	v_add_f32_e32 v87, 1.0, v87
	v_add_f32_e32 v88, 1.0, v88
	v_rcp_f32_e32 v89, v89
	v_rcp_f32_e32 v82, v82
	v_rcp_f32_e32 v83, v83
	v_rcp_f32_e32 v84, v84
	v_rcp_f32_e32 v85, v85
	v_rcp_f32_e32 v86, v86
	v_rcp_f32_e32 v87, v87
	v_rcp_f32_e32 v88, v88
	v_mul_f32_e32 v67, v67, v89
	v_mul_f32_e32 v81, v81, v82
	v_mul_f32_e32 v73, v73, v83
	v_mul_f32_e32 v77, v77, v84
	v_mul_f32_e32 v75, v75, v85
	v_mul_f32_e32 v79, v79, v86
	v_mul_f32_e32 v65, v65, v87
	v_mul_f32_e32 v69, v69, v88
	v_mul_f32_e32 v67, v66, v67
	v_mul_f32_e32 v80, v80, v81
	v_mul_f32_e32 v72, v72, v73
	v_mul_f32_e32 v73, v76, v77
	v_mul_f32_e32 v74, v74, v75
	v_mul_f32_e32 v75, v78, v79
	v_mul_f32_e32 v76, v64, v65
	v_mul_f32_e32 v68, v68, v69
	v_cvt_pk_bf16_f32 v64, v80, v72
	v_cvt_pk_bf16_f32 v65, v73, v74
	v_cvt_pk_bf16_f32 v66, v75, v76
	v_cvt_pk_bf16_f32 v67, v68, v67
	global_store_dwordx4 v[70:71], v[64:67], off
	s_andn2_b64 vcc, exec, s[4:5]
	s_mov_b64 s[0:1], -1
	s_mov_b32 s98, 1
	s_cbranch_vccnz .LBB0_778
	s_andn2_b64 vcc, exec, s[2:3]
	s_cbranch_vccnz .LBB0_777
	s_barrier
	s_branch .LBB0_777
; __device__ __forceinline__ unsigned pk2(float lo, float hi) { return pg8::cvt_pk_bf16(lo, hi); }
; __device__ __forceinline__ float silu_f(float x) { return x * sigmoid_f(x); }
;     __device__ __forceinline__ void operator()(const f32x4 (&acc)[2][2][4][2], const pg8::Unit& u, int wr, int wc, int fr, int fq) const {
;     ...
;         for (int ai = 0; ai < 2; ++ai)
; #pragma unroll
;             for (int m = 0; m < 4; ++m) {
;                 const int row = row0 + ai * 128 + m * 16;
;                 const float rs = sumsq ? rsqrtf(sumsq[row] * (1.f / 1024.f) + EPS) : 1.f;
;                 float o[8];
; #pragma unroll
;                 for (int n = 0; n < 2; ++n)
; #pragma unroll
;                     for (int e = 0; e < 4; ++e) { const float g = acc[ai][0][m][n][e] * rs, up = acc[ai][1][m][n][e] * rs; o[4 * n + e] = silu_f(g) * up; }
;                 u32x4 w; w.x = pk2(o[0], o[1]); w.y = pk2(o[2], o[3]); w.z = pk2(o[4], o[5]); w.w = pk2(o[6], o[7]);
;                 *(u32x4*)(H + (size_t)row * DFF + col) = w;
.Lp6_tail:
	s_nop 0
	s_nop 0
	v_mov_b32_e32 v65, v56
	v_mov_b32_e32 v56, v61
	v_mov_b32_e32 v61, v58
	v_mov_b32_e32 v58, v63
	v_mov_b32_e32 v63, v48
	v_mov_b32_e32 v48, v53
	v_mov_b32_e32 v53, v50
	v_mov_b32_e32 v50, v55
	v_mov_b32_e32 v64, v60
	v_mov_b32_e32 v60, v62
	v_mov_b32_e32 v62, v52
	v_mov_b32_e32 v52, v54
	v_add_u32_e32 v54, 0x80, v228
	s_nop 0
	v_fmamk_f32 v55, v239, 0x3a800000, v154
	v_mul_f32_e32 v66, 0x4b800000, v55
	v_cmp_gt_f32_e32 vcc, s45, v55
	s_nop 1
	v_cndmask_b32_e32 v55, v55, v66, vcc
	v_rsq_f32_e32 v66, v55
	v_mad_i64_i32 v[54:55], s[100:101], v54, s46, v[120:121]
	v_lshl_add_u64 v[54:55], v[54:55], 0, v[122:123]
	v_mul_f32_e32 v67, 0x45800000, v66
	v_cndmask_b32_e32 v66, v66, v67, vcc
	v_pk_mul_f32 v[50:51], v[50:51], v[66:67] op_sel_hi:[1,0]
	v_pk_mul_f32 v[64:65], v[64:65], v[66:67] op_sel_hi:[1,0]
	v_pk_mul_f32 v[56:57], v[56:57], v[66:67] op_sel_hi:[1,0]
	v_pk_mul_f32 v[60:61], v[60:61], v[66:67] op_sel_hi:[1,0]
	v_pk_mul_f32 v[58:59], v[58:59], v[66:67] op_sel_hi:[1,0]
	v_pk_mul_f32 v[62:63], v[62:63], v[66:67] op_sel_hi:[1,0]
	v_pk_mul_f32 v[48:49], v[48:49], v[66:67] op_sel_hi:[1,0]
	v_pk_mul_f32 v[52:53], v[52:53], v[66:67] op_sel_hi:[1,0]
	v_mul_f32_e32 v73, 0xbfb8aa3b, v51
	v_mul_f32_e32 v66, 0xbfb8aa3b, v65
	v_mul_f32_e32 v67, 0xbfb8aa3b, v57
	v_mul_f32_e32 v68, 0xbfb8aa3b, v61
	v_mul_f32_e32 v69, 0xbfb8aa3b, v59
	v_mul_f32_e32 v70, 0xbfb8aa3b, v63
	v_mul_f32_e32 v71, 0xbfb8aa3b, v49
	v_mul_f32_e32 v72, 0xbfb8aa3b, v53
	v_exp_f32_e32 v73, v73
	v_exp_f32_e32 v66, v66
	v_exp_f32_e32 v67, v67
	v_exp_f32_e32 v68, v68
	v_exp_f32_e32 v69, v69
	v_exp_f32_e32 v70, v70
	v_exp_f32_e32 v71, v71
	v_exp_f32_e32 v72, v72
	v_add_f32_e32 v73, 1.0, v73
	v_add_f32_e32 v66, 1.0, v66
	v_add_f32_e32 v67, 1.0, v67
	v_add_f32_e32 v68, 1.0, v68
	v_add_f32_e32 v69, 1.0, v69
	v_add_f32_e32 v70, 1.0, v70
	v_add_f32_e32 v71, 1.0, v71
	v_add_f32_e32 v72, 1.0, v72
	v_rcp_f32_e32 v73, v73
	v_rcp_f32_e32 v66, v66
	v_rcp_f32_e32 v67, v67
	v_rcp_f32_e32 v68, v68
	v_rcp_f32_e32 v69, v69
	v_rcp_f32_e32 v70, v70
	v_rcp_f32_e32 v71, v71
	v_rcp_f32_e32 v72, v72
	v_mul_f32_e32 v51, v51, v73
	v_mul_f32_e32 v65, v65, v66
	v_mul_f32_e32 v57, v57, v67
	v_mul_f32_e32 v61, v61, v68
	v_mul_f32_e32 v59, v59, v69
	v_mul_f32_e32 v63, v63, v70
	v_mul_f32_e32 v49, v49, v71
	v_mul_f32_e32 v53, v53, v72
	v_mul_f32_e32 v51, v50, v51
	v_mul_f32_e32 v64, v64, v65
	v_mul_f32_e32 v56, v56, v57
	v_mul_f32_e32 v57, v60, v61
	v_mul_f32_e32 v58, v58, v59
	v_mul_f32_e32 v59, v62, v63
	v_mul_f32_e32 v60, v48, v49
	v_mul_f32_e32 v52, v52, v53
	v_cvt_pk_bf16_f32 v48, v64, v56
	v_cvt_pk_bf16_f32 v49, v57, v58
	v_cvt_pk_bf16_f32 v50, v59, v60
	v_cvt_pk_bf16_f32 v51, v52, v51
	global_store_dwordx4 v[54:55], v[48:51], off
	s_nop 0
	s_nop 0
	v_mov_b32_e32 v49, v40
	v_mov_b32_e32 v40, v45
	v_mov_b32_e32 v45, v42
	v_mov_b32_e32 v42, v47
	v_mov_b32_e32 v47, v32
	v_mov_b32_e32 v32, v37
	v_mov_b32_e32 v37, v34
	v_mov_b32_e32 v34, v39
	v_mov_b32_e32 v48, v44
	v_mov_b32_e32 v44, v46
	v_mov_b32_e32 v46, v36
	v_mov_b32_e32 v36, v38
	v_add_u32_e32 v38, 0x90, v228
	s_nop 0
	v_fmamk_f32 v39, v240, 0x3a800000, v154
	v_mul_f32_e32 v50, 0x4b800000, v39
	v_cmp_gt_f32_e32 vcc, s45, v39
	s_nop 1
	v_cndmask_b32_e32 v39, v39, v50, vcc
	v_rsq_f32_e32 v50, v39
	v_mad_i64_i32 v[38:39], s[100:101], v38, s46, v[120:121]
	v_lshl_add_u64 v[38:39], v[38:39], 0, v[122:123]
	v_mul_f32_e32 v51, 0x45800000, v50
	v_cndmask_b32_e32 v50, v50, v51, vcc
	v_pk_mul_f32 v[34:35], v[34:35], v[50:51] op_sel_hi:[1,0]
	v_pk_mul_f32 v[48:49], v[48:49], v[50:51] op_sel_hi:[1,0]
	v_pk_mul_f32 v[40:41], v[40:41], v[50:51] op_sel_hi:[1,0]
	v_pk_mul_f32 v[44:45], v[44:45], v[50:51] op_sel_hi:[1,0]
	v_pk_mul_f32 v[42:43], v[42:43], v[50:51] op_sel_hi:[1,0]
	v_pk_mul_f32 v[46:47], v[46:47], v[50:51] op_sel_hi:[1,0]
	v_pk_mul_f32 v[32:33], v[32:33], v[50:51] op_sel_hi:[1,0]
	v_pk_mul_f32 v[36:37], v[36:37], v[50:51] op_sel_hi:[1,0]
	v_mul_f32_e32 v57, 0xbfb8aa3b, v35
	v_mul_f32_e32 v50, 0xbfb8aa3b, v49
	v_mul_f32_e32 v51, 0xbfb8aa3b, v41
	v_mul_f32_e32 v52, 0xbfb8aa3b, v45
	v_mul_f32_e32 v53, 0xbfb8aa3b, v43
	v_mul_f32_e32 v54, 0xbfb8aa3b, v47
	v_mul_f32_e32 v55, 0xbfb8aa3b, v33
	v_mul_f32_e32 v56, 0xbfb8aa3b, v37
	v_exp_f32_e32 v57, v57
	v_exp_f32_e32 v50, v50
	v_exp_f32_e32 v51, v51
	v_exp_f32_e32 v52, v52
	v_exp_f32_e32 v53, v53
	v_exp_f32_e32 v54, v54
	v_exp_f32_e32 v55, v55
	v_exp_f32_e32 v56, v56
	v_add_f32_e32 v57, 1.0, v57
	v_add_f32_e32 v50, 1.0, v50
	v_add_f32_e32 v51, 1.0, v51
	v_add_f32_e32 v52, 1.0, v52
	v_add_f32_e32 v53, 1.0, v53
	v_add_f32_e32 v54, 1.0, v54
	v_add_f32_e32 v55, 1.0, v55
	v_add_f32_e32 v56, 1.0, v56
	v_rcp_f32_e32 v57, v57
	v_rcp_f32_e32 v50, v50
	v_rcp_f32_e32 v51, v51
	v_rcp_f32_e32 v52, v52
	v_rcp_f32_e32 v53, v53
	v_rcp_f32_e32 v54, v54
	v_rcp_f32_e32 v55, v55
	v_rcp_f32_e32 v56, v56
	v_mul_f32_e32 v35, v35, v57
	v_mul_f32_e32 v49, v49, v50
	v_mul_f32_e32 v41, v41, v51
	v_mul_f32_e32 v45, v45, v52
	v_mul_f32_e32 v43, v43, v53
	v_mul_f32_e32 v47, v47, v54
	v_mul_f32_e32 v33, v33, v55
	v_mul_f32_e32 v37, v37, v56
	v_mul_f32_e32 v35, v34, v35
	v_mul_f32_e32 v48, v48, v49
	v_mul_f32_e32 v40, v40, v41
	v_mul_f32_e32 v41, v44, v45
	v_mul_f32_e32 v42, v42, v43
	v_mul_f32_e32 v43, v46, v47
	v_mul_f32_e32 v44, v32, v33
	v_mul_f32_e32 v36, v36, v37
	v_cvt_pk_bf16_f32 v32, v48, v40
	v_cvt_pk_bf16_f32 v33, v41, v42
	v_cvt_pk_bf16_f32 v34, v43, v44
	v_cvt_pk_bf16_f32 v35, v36, v35
; __device__ __forceinline__ unsigned pk2(float lo, float hi) { return pg8::cvt_pk_bf16(lo, hi); }
; __device__ __forceinline__ float silu_f(float x) { return x * sigmoid_f(x); }
;     __device__ __forceinline__ void operator()(const f32x4 (&acc)[2][2][4][2], const pg8::Unit& u, int wr, int wc, int fr, int fq) const {
;     ...
;                 const int row = row0 + ai * 128 + m * 16;
;                 const float rs = sumsq ? rsqrtf(sumsq[row] * (1.f / 1024.f) + EPS) : 1.f;
;                 float o[8];
; #pragma unroll
;                 for (int n = 0; n < 2; ++n)
; #pragma unroll
;                     for (int e = 0; e < 4; ++e) { const float g = acc[ai][0][m][n][e] * rs, up = acc[ai][1][m][n][e] * rs; o[4 * n + e] = silu_f(g) * up; }
;                 u32x4 w; w.x = pk2(o[0], o[1]); w.y = pk2(o[2], o[3]); w.z = pk2(o[4], o[5]); w.w = pk2(o[6], o[7]);
;                 *(u32x4*)(H + (size_t)row * DFF + col) = w;
	global_store_dwordx4 v[38:39], v[32:35], off
	s_nop 0
	s_nop 0
	v_mov_b32_e32 v33, v24
	v_mov_b32_e32 v24, v29
	v_mov_b32_e32 v29, v26
	v_mov_b32_e32 v26, v31
	v_mov_b32_e32 v31, v16
	v_mov_b32_e32 v16, v21
	v_mov_b32_e32 v21, v18
	v_mov_b32_e32 v18, v23
	v_mov_b32_e32 v32, v28
	v_mov_b32_e32 v28, v30
	v_mov_b32_e32 v30, v20
	v_mov_b32_e32 v20, v22
	v_add_u32_e32 v22, 0xa0, v228
	s_nop 0
	v_fmamk_f32 v23, v241, 0x3a800000, v154
	v_mul_f32_e32 v34, 0x4b800000, v23
	v_cmp_gt_f32_e32 vcc, s45, v23
	s_nop 1
	v_cndmask_b32_e32 v23, v23, v34, vcc
	v_rsq_f32_e32 v34, v23
	v_mad_i64_i32 v[22:23], s[100:101], v22, s46, v[120:121]
	v_lshl_add_u64 v[22:23], v[22:23], 0, v[122:123]
	v_mul_f32_e32 v35, 0x45800000, v34
	v_cndmask_b32_e32 v34, v34, v35, vcc
	v_pk_mul_f32 v[18:19], v[18:19], v[34:35] op_sel_hi:[1,0]
	v_pk_mul_f32 v[32:33], v[32:33], v[34:35] op_sel_hi:[1,0]
	v_pk_mul_f32 v[24:25], v[24:25], v[34:35] op_sel_hi:[1,0]
	v_pk_mul_f32 v[28:29], v[28:29], v[34:35] op_sel_hi:[1,0]
	v_pk_mul_f32 v[26:27], v[26:27], v[34:35] op_sel_hi:[1,0]
	v_pk_mul_f32 v[30:31], v[30:31], v[34:35] op_sel_hi:[1,0]
	v_pk_mul_f32 v[16:17], v[16:17], v[34:35] op_sel_hi:[1,0]
	v_pk_mul_f32 v[20:21], v[20:21], v[34:35] op_sel_hi:[1,0]
	v_mul_f32_e32 v41, 0xbfb8aa3b, v19
	v_mul_f32_e32 v34, 0xbfb8aa3b, v33
	v_mul_f32_e32 v35, 0xbfb8aa3b, v25
	v_mul_f32_e32 v36, 0xbfb8aa3b, v29
	v_mul_f32_e32 v37, 0xbfb8aa3b, v27
	v_mul_f32_e32 v38, 0xbfb8aa3b, v31
	v_mul_f32_e32 v39, 0xbfb8aa3b, v17
	v_mul_f32_e32 v40, 0xbfb8aa3b, v21
	v_exp_f32_e32 v41, v41
	v_exp_f32_e32 v34, v34
	v_exp_f32_e32 v35, v35
	v_exp_f32_e32 v36, v36
	v_exp_f32_e32 v37, v37
	v_exp_f32_e32 v38, v38
	v_exp_f32_e32 v39, v39
	v_exp_f32_e32 v40, v40
	v_add_f32_e32 v41, 1.0, v41
	v_add_f32_e32 v34, 1.0, v34
	v_add_f32_e32 v35, 1.0, v35
	v_add_f32_e32 v36, 1.0, v36
	v_add_f32_e32 v37, 1.0, v37
	v_add_f32_e32 v38, 1.0, v38
	v_add_f32_e32 v39, 1.0, v39
	v_add_f32_e32 v40, 1.0, v40
	v_rcp_f32_e32 v41, v41
	v_rcp_f32_e32 v34, v34
	v_rcp_f32_e32 v35, v35
	v_rcp_f32_e32 v36, v36
	v_rcp_f32_e32 v37, v37
	v_rcp_f32_e32 v38, v38
	v_rcp_f32_e32 v39, v39
	v_rcp_f32_e32 v40, v40
	v_mul_f32_e32 v19, v19, v41
	v_mul_f32_e32 v33, v33, v34
	v_mul_f32_e32 v25, v25, v35
	v_mul_f32_e32 v29, v29, v36
	v_mul_f32_e32 v27, v27, v37
	v_mul_f32_e32 v31, v31, v38
	v_mul_f32_e32 v17, v17, v39
	v_mul_f32_e32 v21, v21, v40
	v_mul_f32_e32 v19, v18, v19
	v_mul_f32_e32 v32, v32, v33
	v_mul_f32_e32 v24, v24, v25
	v_mul_f32_e32 v25, v28, v29
	v_mul_f32_e32 v26, v26, v27
	v_mul_f32_e32 v27, v30, v31
	v_mul_f32_e32 v28, v16, v17
	v_mul_f32_e32 v20, v20, v21
	v_cvt_pk_bf16_f32 v16, v32, v24
	v_cvt_pk_bf16_f32 v17, v25, v26
	v_cvt_pk_bf16_f32 v18, v27, v28
	v_cvt_pk_bf16_f32 v19, v20, v19
	global_store_dwordx4 v[22:23], v[16:19], off
	s_nop 0
	v_mov_b32_e32 v17, v8
	v_mov_b32_e32 v8, v13
	v_mov_b32_e32 v13, v10
	v_mov_b32_e32 v10, v15
	v_mov_b32_e32 v15, v0
	v_mov_b32_e32 v0, v5
	v_mov_b32_e32 v5, v2
	v_mov_b32_e32 v2, v7
	v_mov_b32_e32 v16, v12
	v_mov_b32_e32 v12, v14
	v_mov_b32_e32 v14, v4
	v_mov_b32_e32 v4, v6
	v_add_u32_e32 v6, 0xb0, v228
	s_nop 0
	v_fmamk_f32 v7, v242, 0x3a800000, v154
	v_mul_f32_e32 v18, 0x4b800000, v7
	v_cmp_gt_f32_e64 vcc, s45, v7
	s_nop 1
	v_cndmask_b32_e64 v7, v7, v18, vcc
	v_rsq_f32_e32 v18, v7
	v_mad_i64_i32 v[6:7], s[100:101], v6, s46, v[120:121]
	v_lshl_add_u64 v[6:7], v[6:7], 0, v[122:123]
	v_mul_f32_e32 v19, 0x45800000, v18
	v_cndmask_b32_e64 v18, v18, v19, vcc
	v_pk_mul_f32 v[2:3], v[2:3], v[18:19] op_sel_hi:[1,0]
	v_pk_mul_f32 v[16:17], v[16:17], v[18:19] op_sel_hi:[1,0]
	v_pk_mul_f32 v[8:9], v[8:9], v[18:19] op_sel_hi:[1,0]
	v_pk_mul_f32 v[12:13], v[12:13], v[18:19] op_sel_hi:[1,0]
	v_pk_mul_f32 v[10:11], v[10:11], v[18:19] op_sel_hi:[1,0]
	v_pk_mul_f32 v[14:15], v[14:15], v[18:19] op_sel_hi:[1,0]
	v_pk_mul_f32 v[0:1], v[0:1], v[18:19] op_sel_hi:[1,0]
	v_pk_mul_f32 v[4:5], v[4:5], v[18:19] op_sel_hi:[1,0]
	v_mul_f32_e32 v25, 0xbfb8aa3b, v3
	v_mul_f32_e32 v18, 0xbfb8aa3b, v17
	v_mul_f32_e32 v19, 0xbfb8aa3b, v9
	v_mul_f32_e32 v20, 0xbfb8aa3b, v13
	v_mul_f32_e32 v21, 0xbfb8aa3b, v11
	v_mul_f32_e32 v22, 0xbfb8aa3b, v15
	v_mul_f32_e32 v23, 0xbfb8aa3b, v1
	v_mul_f32_e32 v24, 0xbfb8aa3b, v5
	v_exp_f32_e32 v25, v25
	v_exp_f32_e32 v18, v18
	v_exp_f32_e32 v19, v19
	v_exp_f32_e32 v20, v20
	v_exp_f32_e32 v21, v21
	v_exp_f32_e32 v22, v22
	v_exp_f32_e32 v23, v23
	v_exp_f32_e32 v24, v24
	v_add_f32_e32 v25, 1.0, v25
	v_add_f32_e32 v18, 1.0, v18
	v_add_f32_e32 v19, 1.0, v19
	v_add_f32_e32 v20, 1.0, v20
	v_add_f32_e32 v21, 1.0, v21
	v_add_f32_e32 v22, 1.0, v22
	v_add_f32_e32 v23, 1.0, v23
	v_add_f32_e32 v24, 1.0, v24
	v_rcp_f32_e32 v25, v25
	v_rcp_f32_e32 v18, v18
	v_rcp_f32_e32 v19, v19
	v_rcp_f32_e32 v20, v20
	v_rcp_f32_e32 v21, v21
	v_rcp_f32_e32 v22, v22
	v_rcp_f32_e32 v23, v23
	v_rcp_f32_e32 v24, v24
	v_mul_f32_e32 v3, v3, v25
	v_mul_f32_e32 v17, v17, v18
	v_mul_f32_e32 v9, v9, v19
	v_mul_f32_e32 v13, v13, v20
	v_mul_f32_e32 v11, v11, v21
	v_mul_f32_e32 v15, v15, v22
	v_mul_f32_e32 v1, v1, v23
	v_mul_f32_e32 v5, v5, v24
	v_mul_f32_e32 v3, v2, v3
	v_mul_f32_e32 v16, v16, v17
	v_mul_f32_e32 v8, v8, v9
	v_mul_f32_e32 v9, v12, v13
	v_mul_f32_e32 v10, v10, v11
	v_mul_f32_e32 v11, v14, v15
	v_mul_f32_e32 v12, v0, v1
	v_mul_f32_e32 v4, v4, v5
	v_cvt_pk_bf16_f32 v0, v16, v8
	v_cvt_pk_bf16_f32 v1, v9, v10
	v_cvt_pk_bf16_f32 v2, v11, v12
	v_cvt_pk_bf16_f32 v3, v4, v3
	global_store_dwordx4 v[6:7], v[0:3], off
